# GEMM K-loops: first 4 MFMAs of each MFMA phase issued before the phase-opening barrier (barrier latency overlapped with matrix work)
# baseline (speedup 1.0000x reference)
; #define PG8_STAGE(bufoff, gbase, voff) do { _Pragma("unroll") for (int _i = 0; _i < 2; ++_i) \
;         __builtin_amdgcn_global_load_lds((const unsigned*)((const char*)(gbase) + (voff)[_i]), (PG8_LAS unsigned*)(lds + (bufoff) + ldsw + _i * 8192), 16, 0, 0); } while (0)
; #define PG8_LDA(dst, b, h) do { _Pragma("unroll") for (int m = 0; m < 4; ++m) _Pragma("unroll") for (int k = 0; k < 2; ++k) dst[m][k] = *(const PG8_LAS bf16x8*)(lds + PG8_SA(b, h) + aoff + m * 2048 + k * 1024); } while (0)
; #define PG8_LDB(dst, b, h) do { _Pragma("unroll") for (int n = 0; n < 2; ++n) _Pragma("unroll") for (int k = 0; k < 2; ++k) dst[n][k] = *(const PG8_LAS bf16x8*)(lds + PG8_SB(b, h) + boff + n * 2048 + k * 1024); } while (0)
; #define PG8_MMA(ai, bj, At, Bt) do { __builtin_amdgcn_s_setprio(1); _Pragma("unroll") for (int m = 0; m < 4; ++m) _Pragma("unroll") for (int n = 0; n < 2; ++n) _Pragma("unroll") for (int k = 0; k < 2; ++k) \
;         acc[ai][bj][m][n] = __builtin_amdgcn_mfma_f32_16x16x32_bf16(Bt[n][k], At[m][k], acc[ai][bj][m][n], 0, 0, 0); __builtin_amdgcn_s_setprio(0); } while (0)
; #define PG8_WAIT_V(n) asm volatile("s_waitcnt vmcnt(" #n ")" ::: "memory")
; #define PG8_WAIT_L(n) asm volatile("s_waitcnt lgkmcnt(" #n ")" ::: "memory")
; template <class Epi, class Sched, bool ALIGN_EPI = false, bool SP2 = false>
; __device__ __forceinline__ void gemm_phase(PG8_LAS unsigned char* lds, const Gemm g, const Sched& S, const Epi& E, const int tid) {
;     ...
;             const bool last = (t == nt - 2);
;             const char* a1 = cA + (size_t)(t + 1) * kstep;
;             const char* a2 = last ? nA : cA + (size_t)(t + 2) * kstep; const char* b2 = last ? nB : cB + (size_t)(t + 2) * kstep;
;             const char* a3 = a2 + kstep; const char* b3 = b2 + kstep;
;             if (last && has_next) S.a_ready(nxt);
;             if constexpr (SP2) {
;             PG8_LDB(B0, 0, 0); PG8_LDB(B1, 0, 1); PG8_SCHED; PG8_LDA(At, 0, 0); PG8_STAGE(PG8_SA(1, 1), a1 + hstep, voffA);
;             PG8_WAIT_V(8); PG8_WAIT_L(0); PG8_BAR; PG8_MMA(0, 0, At, B0); PG8_MMA(0, 1, At, B1); PG8_BAR; PG8_SCHED;
;             PG8_LDA(At, 0, 1); PG8_STAGE(PG8_SB(0, 0), b2, voffB); PG8_STAGE(PG8_SB(0, 1), b2 + hstep, voffB); PG8_STAGE(PG8_SA(0, 0), a2, voffA);
;             PG8_WAIT_V(8); PG8_WAIT_L(0); PG8_BAR; PG8_MMA(1, 0, At, B0); PG8_MMA(1, 1, At, B1); PG8_BAR; PG8_SCHED;
.LBB0_211:
	s_add_u32 s56, s54, 0xfff80080
	s_addc_u32 s57, s55, -1
	s_add_i32 s78, 0, 0x10000
	s_cmp_eq_u32 s77, 28
	s_cselect_b32 s59, s49, s57
	s_cselect_b32 s58, s72, s56
	s_cselect_b32 s57, s47, s76
	s_cselect_b32 s56, s73, s75
	s_add_i32 s80, 0, 0x14000
	v_add_u32_e32 v154, s78, v160
	v_add_u32_e32 v158, s80, v160
	ds_read_b128 v[142:145], v154
	ds_read_b128 v[146:149], v154 offset:1024
	ds_read_b128 v[150:153], v154 offset:2048
	ds_read_b128 v[154:157], v154 offset:3072
	ds_read_b128 v[164:167], v158
	ds_read_b128 v[168:171], v158 offset:1024
	ds_read_b128 v[172:175], v158 offset:2048
	ds_read_b128 v[176:179], v158 offset:3072
	v_lshl_add_u64 v[158:159], s[54:55], 0, v[140:141]
	s_add_i32 m0, s61, 0xc000
	ds_read_b128 v[186:189], v162
	ds_read_b128 v[190:193], v162 offset:1024
	ds_read_b128 v[194:197], v162 offset:2048
	ds_read_b128 v[198:201], v162 offset:3072
	ds_read_b128 v[202:205], v162 offset:4096
	ds_read_b128 v[206:209], v162 offset:5120
	ds_read_b128 v[210:213], v162 offset:6144
	ds_read_b128 v[214:217], v162 offset:7168
	global_load_lds_dwordx4 v[158:159], off
	v_lshl_add_u64 v[158:159], s[54:55], 0, v[138:139]
	s_add_i32 m0, s61, 0xe000
	s_nop 0
	global_load_lds_dwordx4 v[158:159], off
	s_waitcnt vmcnt(8)
	s_waitcnt lgkmcnt(0)
	s_setprio 1
	v_mfma_f32_16x16x32_bf16 v[130:133], v[142:145], v[186:189], v[130:133]
	v_mfma_f32_16x16x32_bf16 v[126:129], v[150:153], v[186:189], v[126:129]
	v_mfma_f32_16x16x32_bf16 v[114:117], v[142:145], v[194:197], v[114:117]
	v_mfma_f32_16x16x32_bf16 v[106:109], v[150:153], v[194:197], v[106:109]
	s_barrier
	v_mfma_f32_16x16x32_bf16 v[92:95], v[142:145], v[202:205], v[92:95]
	v_mfma_f32_16x16x32_bf16 v[84:87], v[150:153], v[202:205], v[84:87]
	v_mfma_f32_16x16x32_bf16 v[76:79], v[142:145], v[210:213], v[76:79]
	v_mfma_f32_16x16x32_bf16 v[68:71], v[150:153], v[210:213], v[68:71]
	v_mfma_f32_16x16x32_bf16 v[130:133], v[146:149], v[190:193], v[130:133]
	v_mfma_f32_16x16x32_bf16 v[126:129], v[154:157], v[190:193], v[126:129]
	v_mfma_f32_16x16x32_bf16 v[114:117], v[146:149], v[198:201], v[114:117]
	v_mfma_f32_16x16x32_bf16 v[106:109], v[154:157], v[198:201], v[106:109]
	v_mfma_f32_16x16x32_bf16 v[92:95], v[146:149], v[206:209], v[92:95]
	v_mfma_f32_16x16x32_bf16 v[84:87], v[154:157], v[206:209], v[84:87]
	v_mfma_f32_16x16x32_bf16 v[76:79], v[146:149], v[214:217], v[76:79]
	v_mfma_f32_16x16x32_bf16 v[68:71], v[154:157], v[214:217], v[68:71]
	v_mfma_f32_16x16x32_bf16 v[122:125], v[164:167], v[186:189], v[122:125]
	v_mfma_f32_16x16x32_bf16 v[118:121], v[172:175], v[186:189], v[118:121]
	v_mfma_f32_16x16x32_bf16 v[110:113], v[164:167], v[194:197], v[110:113]
	v_mfma_f32_16x16x32_bf16 v[102:105], v[172:175], v[194:197], v[102:105]
	v_mfma_f32_16x16x32_bf16 v[88:91], v[164:167], v[202:205], v[88:91]
	v_mfma_f32_16x16x32_bf16 v[80:83], v[172:175], v[202:205], v[80:83]
	v_mfma_f32_16x16x32_bf16 v[72:75], v[164:167], v[210:213], v[72:75]
	v_mfma_f32_16x16x32_bf16 v[64:67], v[172:175], v[210:213], v[64:67]
	v_mfma_f32_16x16x32_bf16 v[122:125], v[168:171], v[190:193], v[122:125]
	v_mfma_f32_16x16x32_bf16 v[118:121], v[176:179], v[190:193], v[118:121]
	v_mfma_f32_16x16x32_bf16 v[110:113], v[168:171], v[198:201], v[110:113]
	v_mfma_f32_16x16x32_bf16 v[102:105], v[176:179], v[198:201], v[102:105]
	v_mfma_f32_16x16x32_bf16 v[88:91], v[168:171], v[206:209], v[88:91]
	v_mfma_f32_16x16x32_bf16 v[80:83], v[176:179], v[206:209], v[80:83]
	v_mfma_f32_16x16x32_bf16 v[72:75], v[168:171], v[214:217], v[72:75]
	v_mfma_f32_16x16x32_bf16 v[64:67], v[176:179], v[214:217], v[64:67]
	s_barrier
	s_setprio 0
	s_add_i32 s78, s78, s60
	v_lshl_add_u64 v[158:159], s[56:57], 0, v[96:97]
	s_mov_b32 m0, s78
	ds_read_b128 v[186:189], v162 offset:16384
	ds_read_b128 v[190:193], v162 offset:17408
	ds_read_b128 v[194:197], v162 offset:18432
	ds_read_b128 v[198:201], v162 offset:19456
	ds_read_b128 v[202:205], v162 offset:20480
	ds_read_b128 v[206:209], v162 offset:21504
	ds_read_b128 v[210:213], v162 offset:22528
	ds_read_b128 v[214:217], v162 offset:23552
	global_load_lds_dwordx4 v[158:159], off
	s_add_i32 m0, s78, 0x2000
	s_add_u32 s78, s56, 0x80000
	v_lshl_add_u64 v[180:181], s[56:57], 0, v[98:99]
	s_addc_u32 s79, s57, 0
	s_add_i32 s80, s80, s60
	global_load_lds_dwordx4 v[180:181], off
	v_lshl_add_u64 v[218:219], s[78:79], 0, v[96:97]
	s_mov_b32 m0, s80
	v_lshl_add_u64 v[220:221], s[58:59], 0, v[134:135]
	global_load_lds_dwordx4 v[218:219], off
	v_lshl_add_u64 v[218:219], s[78:79], 0, v[98:99]
	s_add_i32 m0, s80, 0x2000
	s_nop 0
	global_load_lds_dwordx4 v[218:219], off
	v_lshl_add_u64 v[218:219], s[58:59], 0, v[136:137]
	s_mov_b32 m0, s61
	s_nop 0
	global_load_lds_dwordx4 v[218:219], off
	s_mov_b32 m0, s64
	s_nop 0
	global_load_lds_dwordx4 v[220:221], off
	s_waitcnt vmcnt(8)
	s_waitcnt lgkmcnt(0)
	s_setprio 1
	v_mfma_f32_16x16x32_bf16 v[60:63], v[142:145], v[186:189], v[60:63]
	v_mfma_f32_16x16x32_bf16 v[52:55], v[150:153], v[186:189], v[52:55]
	v_mfma_f32_16x16x32_bf16 v[44:47], v[142:145], v[194:197], v[44:47]
	v_mfma_f32_16x16x32_bf16 v[36:39], v[150:153], v[194:197], v[36:39]
	s_barrier
; #define PG8_STAGE(bufoff, gbase, voff) do { _Pragma("unroll") for (int _i = 0; _i < 2; ++_i) \
;         __builtin_amdgcn_global_load_lds((const unsigned*)((const char*)(gbase) + (voff)[_i]), (PG8_LAS unsigned*)(lds + (bufoff) + ldsw + _i * 8192), 16, 0, 0); } while (0)
; #define PG8_LDA(dst, b, h) do { _Pragma("unroll") for (int m = 0; m < 4; ++m) _Pragma("unroll") for (int k = 0; k < 2; ++k) dst[m][k] = *(const PG8_LAS bf16x8*)(lds + PG8_SA(b, h) + aoff + m * 2048 + k * 1024); } while (0)
; #define PG8_LDB(dst, b, h) do { _Pragma("unroll") for (int n = 0; n < 2; ++n) _Pragma("unroll") for (int k = 0; k < 2; ++k) dst[n][k] = *(const PG8_LAS bf16x8*)(lds + PG8_SB(b, h) + boff + n * 2048 + k * 1024); } while (0)
; #define PG8_MMA(ai, bj, At, Bt) do { __builtin_amdgcn_s_setprio(1); _Pragma("unroll") for (int m = 0; m < 4; ++m) _Pragma("unroll") for (int n = 0; n < 2; ++n) _Pragma("unroll") for (int k = 0; k < 2; ++k) \
;         acc[ai][bj][m][n] = __builtin_amdgcn_mfma_f32_16x16x32_bf16(Bt[n][k], At[m][k], acc[ai][bj][m][n], 0, 0, 0); __builtin_amdgcn_s_setprio(0); } while (0)
; #define PG8_WAIT_V(n) asm volatile("s_waitcnt vmcnt(" #n ")" ::: "memory")
; #define PG8_WAIT_L(n) asm volatile("s_waitcnt lgkmcnt(" #n ")" ::: "memory")
; #define PG8_BAR __builtin_amdgcn_s_barrier()
; #define PG8_SCHED __builtin_amdgcn_sched_barrier(0)
; template <class Epi, class Sched, bool ALIGN_EPI = false, bool SP2 = false>
; __device__ __forceinline__ void gemm_phase(PG8_LAS unsigned char* lds, const Gemm g, const Sched& S, const Epi& E, const int tid) {
;     ...
;             PG8_WAIT_V(8); PG8_WAIT_L(0); PG8_BAR; PG8_MMA(0, 0, At, B0); PG8_MMA(0, 1, At, B1); PG8_BAR; PG8_SCHED;
;             PG8_LDA(At, 0, 1); PG8_STAGE(PG8_SB(0, 0), b2, voffB); PG8_STAGE(PG8_SB(0, 1), b2 + hstep, voffB); PG8_STAGE(PG8_SA(0, 0), a2, voffA);
;             PG8_WAIT_V(8); PG8_WAIT_L(0); PG8_BAR; PG8_MMA(1, 0, At, B0); PG8_MMA(1, 1, At, B1); PG8_BAR; PG8_SCHED;
;             PG8_LDB(B0, 1, 0); PG8_LDB(B1, 1, 1); PG8_SCHED; PG8_LDA(At, 1, 0); PG8_STAGE(PG8_SA(0, 1), a2 + hstep, voffA);
;             PG8_WAIT_V(8); PG8_WAIT_L(0); PG8_BAR; PG8_MMA(0, 0, At, B0); PG8_MMA(0, 1, At, B1); PG8_BAR; PG8_SCHED;
	v_mfma_f32_16x16x32_bf16 v[28:31], v[142:145], v[202:205], v[28:31]
	v_mfma_f32_16x16x32_bf16 v[20:23], v[150:153], v[202:205], v[20:23]
	v_mfma_f32_16x16x32_bf16 v[12:15], v[142:145], v[210:213], v[12:15]
	v_mfma_f32_16x16x32_bf16 v[4:7], v[150:153], v[210:213], v[4:7]
	v_mfma_f32_16x16x32_bf16 v[60:63], v[146:149], v[190:193], v[60:63]
	v_mfma_f32_16x16x32_bf16 v[52:55], v[154:157], v[190:193], v[52:55]
	v_mfma_f32_16x16x32_bf16 v[44:47], v[146:149], v[198:201], v[44:47]
	v_mfma_f32_16x16x32_bf16 v[36:39], v[154:157], v[198:201], v[36:39]
	v_mfma_f32_16x16x32_bf16 v[28:31], v[146:149], v[206:209], v[28:31]
	v_mfma_f32_16x16x32_bf16 v[20:23], v[154:157], v[206:209], v[20:23]
	v_mfma_f32_16x16x32_bf16 v[12:15], v[146:149], v[214:217], v[12:15]
	v_mfma_f32_16x16x32_bf16 v[4:7], v[154:157], v[214:217], v[4:7]
	v_mfma_f32_16x16x32_bf16 v[56:59], v[164:167], v[186:189], v[56:59]
	v_mfma_f32_16x16x32_bf16 v[48:51], v[172:175], v[186:189], v[48:51]
	v_mfma_f32_16x16x32_bf16 v[40:43], v[164:167], v[194:197], v[40:43]
	v_mfma_f32_16x16x32_bf16 v[32:35], v[172:175], v[194:197], v[32:35]
	v_mfma_f32_16x16x32_bf16 v[24:27], v[164:167], v[202:205], v[24:27]
	v_mfma_f32_16x16x32_bf16 v[16:19], v[172:175], v[202:205], v[16:19]
	v_mfma_f32_16x16x32_bf16 v[8:11], v[164:167], v[210:213], v[8:11]
	v_mfma_f32_16x16x32_bf16 v[0:3], v[172:175], v[210:213], v[0:3]
	v_mfma_f32_16x16x32_bf16 v[56:59], v[168:171], v[190:193], v[56:59]
	v_mfma_f32_16x16x32_bf16 v[48:51], v[176:179], v[190:193], v[48:51]
	v_mfma_f32_16x16x32_bf16 v[40:43], v[168:171], v[198:201], v[40:43]
	v_mfma_f32_16x16x32_bf16 v[32:35], v[176:179], v[198:201], v[32:35]
	v_mfma_f32_16x16x32_bf16 v[24:27], v[168:171], v[206:209], v[24:27]
	v_mfma_f32_16x16x32_bf16 v[16:19], v[176:179], v[206:209], v[16:19]
	v_mfma_f32_16x16x32_bf16 v[8:11], v[168:171], v[214:217], v[8:11]
	v_mfma_f32_16x16x32_bf16 v[0:3], v[176:179], v[214:217], v[0:3]
	s_barrier
	s_setprio 0
	s_add_i32 s78, 0, 0x18000
	s_add_i32 s79, 0, 0x1c000
	v_add_u32_e32 v154, s78, v160
	v_add_u32_e32 v163, s79, v160
	ds_read_b128 v[142:145], v154
	ds_read_b128 v[146:149], v154 offset:1024
	ds_read_b128 v[150:153], v154 offset:2048
	ds_read_b128 v[154:157], v154 offset:3072
	ds_read_b128 v[164:167], v163
	ds_read_b128 v[168:171], v163 offset:1024
	ds_read_b128 v[172:175], v163 offset:2048
	ds_read_b128 v[176:179], v163 offset:3072
	s_add_u32 s58, s58, 0x80000
	s_addc_u32 s59, s59, 0
	s_mov_b32 m0, s65
	v_lshl_add_u64 v[222:223], s[58:59], 0, v[136:137]
	ds_read_b128 v[186:189], v162 offset:32768
	ds_read_b128 v[190:193], v162 offset:33792
	ds_read_b128 v[194:197], v162 offset:34816
	ds_read_b128 v[198:201], v162 offset:35840
	ds_read_b128 v[202:205], v162 offset:36864
	ds_read_b128 v[206:209], v162 offset:37888
	ds_read_b128 v[210:213], v162 offset:38912
	ds_read_b128 v[214:217], v162 offset:39936
	global_load_lds_dwordx4 v[222:223], off
	v_lshl_add_u64 v[222:223], s[58:59], 0, v[134:135]
	s_mov_b32 m0, s66
	s_nop 0
	global_load_lds_dwordx4 v[222:223], off
	s_waitcnt vmcnt(8)
	s_waitcnt lgkmcnt(0)
	s_setprio 1
	v_mfma_f32_16x16x32_bf16 v[130:133], v[142:145], v[186:189], v[130:133]
	v_mfma_f32_16x16x32_bf16 v[126:129], v[150:153], v[186:189], v[126:129]
	v_mfma_f32_16x16x32_bf16 v[114:117], v[142:145], v[194:197], v[114:117]
	v_mfma_f32_16x16x32_bf16 v[106:109], v[150:153], v[194:197], v[106:109]
	s_barrier
	v_mfma_f32_16x16x32_bf16 v[92:95], v[142:145], v[202:205], v[92:95]
	v_mfma_f32_16x16x32_bf16 v[84:87], v[150:153], v[202:205], v[84:87]
	v_mfma_f32_16x16x32_bf16 v[76:79], v[142:145], v[210:213], v[76:79]
	v_mfma_f32_16x16x32_bf16 v[68:71], v[150:153], v[210:213], v[68:71]
	v_mfma_f32_16x16x32_bf16 v[130:133], v[146:149], v[190:193], v[130:133]
	v_mfma_f32_16x16x32_bf16 v[126:129], v[154:157], v[190:193], v[126:129]
	v_mfma_f32_16x16x32_bf16 v[114:117], v[146:149], v[198:201], v[114:117]
	v_mfma_f32_16x16x32_bf16 v[106:109], v[154:157], v[198:201], v[106:109]
	v_mfma_f32_16x16x32_bf16 v[92:95], v[146:149], v[206:209], v[92:95]
	v_mfma_f32_16x16x32_bf16 v[84:87], v[154:157], v[206:209], v[84:87]
	v_mfma_f32_16x16x32_bf16 v[76:79], v[146:149], v[214:217], v[76:79]
	v_mfma_f32_16x16x32_bf16 v[68:71], v[154:157], v[214:217], v[68:71]
	v_mfma_f32_16x16x32_bf16 v[122:125], v[164:167], v[186:189], v[122:125]
	v_mfma_f32_16x16x32_bf16 v[118:121], v[172:175], v[186:189], v[118:121]
	v_mfma_f32_16x16x32_bf16 v[110:113], v[164:167], v[194:197], v[110:113]
	v_mfma_f32_16x16x32_bf16 v[102:105], v[172:175], v[194:197], v[102:105]
	v_mfma_f32_16x16x32_bf16 v[88:91], v[164:167], v[202:205], v[88:91]
	v_mfma_f32_16x16x32_bf16 v[80:83], v[172:175], v[202:205], v[80:83]
	v_mfma_f32_16x16x32_bf16 v[72:75], v[164:167], v[210:213], v[72:75]
	v_mfma_f32_16x16x32_bf16 v[64:67], v[172:175], v[210:213], v[64:67]
	v_mfma_f32_16x16x32_bf16 v[122:125], v[168:171], v[190:193], v[122:125]
	v_mfma_f32_16x16x32_bf16 v[118:121], v[176:179], v[190:193], v[118:121]
	v_mfma_f32_16x16x32_bf16 v[110:113], v[168:171], v[198:201], v[110:113]
	v_mfma_f32_16x16x32_bf16 v[102:105], v[176:179], v[198:201], v[102:105]
	v_mfma_f32_16x16x32_bf16 v[88:91], v[168:171], v[206:209], v[88:91]
	v_mfma_f32_16x16x32_bf16 v[80:83], v[176:179], v[206:209], v[80:83]
	v_mfma_f32_16x16x32_bf16 v[72:75], v[168:171], v[214:217], v[72:75]
	v_mfma_f32_16x16x32_bf16 v[64:67], v[176:179], v[214:217], v[64:67]
	s_barrier
; #define PG8_STAGE(bufoff, gbase, voff) do { _Pragma("unroll") for (int _i = 0; _i < 2; ++_i) \
;         __builtin_amdgcn_global_load_lds((const unsigned*)((const char*)(gbase) + (voff)[_i]), (PG8_LAS unsigned*)(lds + (bufoff) + ldsw + _i * 8192), 16, 0, 0); } while (0)
; #define PG8_WAIT_V(n) asm volatile("s_waitcnt vmcnt(" #n ")" ::: "memory")
; #define PG8_WAIT_L(n) asm volatile("s_waitcnt lgkmcnt(" #n ")" ::: "memory")
; template <class Epi, class Sched, bool ALIGN_EPI = false, bool SP2 = false>
; __device__ __forceinline__ void gemm_phase(PG8_LAS unsigned char* lds, const Gemm g, const Sched& S, const Epi& E, const int tid) {
;     ...
;             PG8_WAIT_V(8); PG8_WAIT_L(0); PG8_BAR; PG8_MMA(0, 0, At, B0); PG8_MMA(0, 1, At, B1); PG8_BAR; PG8_SCHED;
;             PG8_LDA(At, 1, 1); PG8_STAGE(PG8_SB(1, 0), b3, voffB); PG8_STAGE(PG8_SB(1, 1), b3 + hstep, voffB); PG8_STAGE(PG8_SA(1, 0), a3, voffA);
;             PG8_WAIT_V(8); PG8_WAIT_L(0); PG8_BAR; PG8_MMA(1, 0, At, B0); PG8_MMA(1, 1, At, B1); PG8_BAR; PG8_SCHED;
;             } else {
;             PG8_LDB(B0, 0, 0); PG8_SCHED; PG8_LDA(At, 0, 0); PG8_STAGE(PG8_SA(1, 1), a1 + hstep, voffA);
;             PG8_WAIT_L(8); PG8_BAR; PG8_WAIT_L(0); PG8_MMA(0, 0, At, B0); PG8_BAR; PG8_SCHED;
;             PG8_LDB(B1, 0, 1); PG8_STAGE(PG8_SB(0, 0), b2, voffB);
;             PG8_BAR; PG8_WAIT_L(0); PG8_MMA(0, 1, At, B1); PG8_BAR;
;             PG8_LDA(At, 0, 1); PG8_STAGE(PG8_SA(0, 0), a2, voffA);
;             PG8_BAR; PG8_WAIT_L(0); PG8_MMA(1, 0, At, B0); PG8_BAR; PG8_SCHED;
;             PG8_STAGE(PG8_SB(0, 1), b2 + hstep, voffB);
;             PG8_WAIT_V(6); PG8_BAR; PG8_MMA(1, 1, At, B1); PG8_BAR;
;             PG8_LDB(B0, 1, 0); PG8_SCHED; PG8_LDA(At, 1, 0); PG8_STAGE(PG8_SA(0, 1), a2 + hstep, voffA);
;             PG8_WAIT_L(8); PG8_BAR; PG8_WAIT_L(0); PG8_MMA(0, 0, At, B0); PG8_BAR; PG8_SCHED;
;             PG8_LDB(B1, 1, 1); PG8_STAGE(PG8_SB(1, 0), b3, voffB);
;             PG8_BAR; PG8_WAIT_L(0); PG8_MMA(0, 1, At, B1); PG8_BAR;
;             PG8_LDA(At, 1, 1); PG8_STAGE(PG8_SA(1, 0), a3, voffA);
;             PG8_BAR; PG8_WAIT_L(0); PG8_MMA(1, 0, At, B0); PG8_BAR; PG8_SCHED;
;             PG8_STAGE(PG8_SB(1, 1), b3 + hstep, voffB);
;             PG8_WAIT_V(6); PG8_BAR; PG8_MMA(1, 1, At, B1); PG8_BAR;
;             }
;         }
;         if constexpr (ALIGN_EPI) { if (wr == 0) PG8_BAR; }
	s_setprio 0
	s_add_i32 s58, s78, s60
	v_lshl_add_u64 v[158:159], v[158:159], 0, s[28:29]
	s_mov_b32 m0, s58
	ds_read_b128 v[186:189], v162 offset:49152
	ds_read_b128 v[190:193], v162 offset:50176
	ds_read_b128 v[194:197], v162 offset:51200
	ds_read_b128 v[198:201], v162 offset:52224
	ds_read_b128 v[202:205], v162 offset:53248
	ds_read_b128 v[206:209], v162 offset:54272
	ds_read_b128 v[210:213], v162 offset:55296
	ds_read_b128 v[214:217], v162 offset:56320
	global_load_lds_dwordx4 v[158:159], off
	s_add_i32 m0, s58, 0x2000
	s_add_u32 s56, s56, 0x80080
	v_lshl_add_u64 v[158:159], v[180:181], 0, s[28:29]
	s_addc_u32 s57, s57, 0
	s_add_i32 s58, s79, s60
	global_load_lds_dwordx4 v[158:159], off
	v_lshl_add_u64 v[158:159], s[56:57], 0, v[96:97]
	s_mov_b32 m0, s58
	s_nop 0
	global_load_lds_dwordx4 v[158:159], off
	v_lshl_add_u64 v[158:159], s[56:57], 0, v[98:99]
	s_add_i32 m0, s58, 0x2000
	s_nop 0
	global_load_lds_dwordx4 v[158:159], off
	v_lshl_add_u64 v[158:159], v[218:219], 0, s[28:29]
	s_mov_b32 m0, s67
	s_nop 0
	global_load_lds_dwordx4 v[158:159], off
	v_lshl_add_u64 v[158:159], v[220:221], 0, s[28:29]
	s_mov_b32 m0, s68
	s_nop 0
	global_load_lds_dwordx4 v[158:159], off
	s_waitcnt vmcnt(8)
	s_waitcnt lgkmcnt(0)
	s_setprio 1
	v_mfma_f32_16x16x32_bf16 v[60:63], v[142:145], v[186:189], v[60:63]
	v_mfma_f32_16x16x32_bf16 v[52:55], v[150:153], v[186:189], v[52:55]
	v_mfma_f32_16x16x32_bf16 v[44:47], v[142:145], v[194:197], v[44:47]
	v_mfma_f32_16x16x32_bf16 v[36:39], v[150:153], v[194:197], v[36:39]
	s_barrier
	v_mfma_f32_16x16x32_bf16 v[28:31], v[142:145], v[202:205], v[28:31]
	v_mfma_f32_16x16x32_bf16 v[20:23], v[150:153], v[202:205], v[20:23]
	v_mfma_f32_16x16x32_bf16 v[12:15], v[142:145], v[210:213], v[12:15]
	v_mfma_f32_16x16x32_bf16 v[4:7], v[150:153], v[210:213], v[4:7]
	v_mfma_f32_16x16x32_bf16 v[60:63], v[146:149], v[190:193], v[60:63]
	v_mfma_f32_16x16x32_bf16 v[52:55], v[154:157], v[190:193], v[52:55]
	v_mfma_f32_16x16x32_bf16 v[44:47], v[146:149], v[198:201], v[44:47]
	v_mfma_f32_16x16x32_bf16 v[36:39], v[154:157], v[198:201], v[36:39]
	v_mfma_f32_16x16x32_bf16 v[28:31], v[146:149], v[206:209], v[28:31]
	v_mfma_f32_16x16x32_bf16 v[20:23], v[154:157], v[206:209], v[20:23]
	v_mfma_f32_16x16x32_bf16 v[12:15], v[146:149], v[214:217], v[12:15]
	v_mfma_f32_16x16x32_bf16 v[4:7], v[154:157], v[214:217], v[4:7]
	v_mfma_f32_16x16x32_bf16 v[56:59], v[164:167], v[186:189], v[56:59]
	v_mfma_f32_16x16x32_bf16 v[48:51], v[172:175], v[186:189], v[48:51]
	v_mfma_f32_16x16x32_bf16 v[40:43], v[164:167], v[194:197], v[40:43]
	v_mfma_f32_16x16x32_bf16 v[32:35], v[172:175], v[194:197], v[32:35]
	v_mfma_f32_16x16x32_bf16 v[24:27], v[164:167], v[202:205], v[24:27]
	v_mfma_f32_16x16x32_bf16 v[16:19], v[172:175], v[202:205], v[16:19]
	v_mfma_f32_16x16x32_bf16 v[8:11], v[164:167], v[210:213], v[8:11]
	v_mfma_f32_16x16x32_bf16 v[0:3], v[172:175], v[210:213], v[0:3]
	v_mfma_f32_16x16x32_bf16 v[56:59], v[168:171], v[190:193], v[56:59]
	v_mfma_f32_16x16x32_bf16 v[48:51], v[176:179], v[190:193], v[48:51]
	v_mfma_f32_16x16x32_bf16 v[40:43], v[168:171], v[198:201], v[40:43]
	v_mfma_f32_16x16x32_bf16 v[32:35], v[176:179], v[198:201], v[32:35]
	v_mfma_f32_16x16x32_bf16 v[24:27], v[168:171], v[206:209], v[24:27]
	v_mfma_f32_16x16x32_bf16 v[16:19], v[176:179], v[206:209], v[16:19]
	v_mfma_f32_16x16x32_bf16 v[8:11], v[168:171], v[214:217], v[8:11]
	v_mfma_f32_16x16x32_bf16 v[0:3], v[176:179], v[214:217], v[0:3]
	s_barrier
	s_setprio 0
	s_add_i32 s77, s77, 2
	s_add_u32 s75, s75, 0x100
	s_addc_u32 s76, s76, 0
	s_add_u32 s54, s54, 0x100
	s_addc_u32 s55, s55, 0
	s_cmp_gt_u32 s77, 29
	s_cbranch_scc0 .LBB0_211
	s_and_b64 vcc, exec, s[44:45]
	s_cbranch_vccz .LBB0_214
	s_barrier

; #define PG8_STAGE(bufoff, gbase, voff) do { _Pragma("unroll") for (int _i = 0; _i < 2; ++_i) \
;         __builtin_amdgcn_global_load_lds((const unsigned*)((const char*)(gbase) + (voff)[_i]), (PG8_LAS unsigned*)(lds + (bufoff) + ldsw + _i * 8192), 16, 0, 0); } while (0)
; #define PG8_LDA(dst, b, h) do { _Pragma("unroll") for (int m = 0; m < 4; ++m) _Pragma("unroll") for (int k = 0; k < 2; ++k) dst[m][k] = *(const PG8_LAS bf16x8*)(lds + PG8_SA(b, h) + aoff + m * 2048 + k * 1024); } while (0)
; #define PG8_LDB(dst, b, h) do { _Pragma("unroll") for (int n = 0; n < 2; ++n) _Pragma("unroll") for (int k = 0; k < 2; ++k) dst[n][k] = *(const PG8_LAS bf16x8*)(lds + PG8_SB(b, h) + boff + n * 2048 + k * 1024); } while (0)
; #define PG8_MMA(ai, bj, At, Bt) do { __builtin_amdgcn_s_setprio(1); _Pragma("unroll") for (int m = 0; m < 4; ++m) _Pragma("unroll") for (int n = 0; n < 2; ++n) _Pragma("unroll") for (int k = 0; k < 2; ++k) \
;         acc[ai][bj][m][n] = __builtin_amdgcn_mfma_f32_16x16x32_bf16(Bt[n][k], At[m][k], acc[ai][bj][m][n], 0, 0, 0); __builtin_amdgcn_s_setprio(0); } while (0)
; #define PG8_WAIT_V(n) asm volatile("s_waitcnt vmcnt(" #n ")" ::: "memory")
; #define PG8_WAIT_L(n) asm volatile("s_waitcnt lgkmcnt(" #n ")" ::: "memory")
; template <class Epi, class Sched, bool ALIGN_EPI = false, bool SP2 = false>
; __device__ __forceinline__ void gemm_phase(PG8_LAS unsigned char* lds, const Gemm g, const Sched& S, const Epi& E, const int tid) {
;     ...
;             const bool last = (t == nt - 2);
;             const char* a1 = cA + (size_t)(t + 1) * kstep;
;             const char* a2 = last ? nA : cA + (size_t)(t + 2) * kstep; const char* b2 = last ? nB : cB + (size_t)(t + 2) * kstep;
;             const char* a3 = a2 + kstep; const char* b3 = b2 + kstep;
;             if (last && has_next) S.a_ready(nxt);
;             if constexpr (SP2) {
;             PG8_LDB(B0, 0, 0); PG8_LDB(B1, 0, 1); PG8_SCHED; PG8_LDA(At, 0, 0); PG8_STAGE(PG8_SA(1, 1), a1 + hstep, voffA);
;             PG8_WAIT_V(8); PG8_WAIT_L(0); PG8_BAR; PG8_MMA(0, 0, At, B0); PG8_MMA(0, 1, At, B1); PG8_BAR; PG8_SCHED;
;             PG8_LDA(At, 0, 1); PG8_STAGE(PG8_SB(0, 0), b2, voffB); PG8_STAGE(PG8_SB(0, 1), b2 + hstep, voffB); PG8_STAGE(PG8_SA(0, 0), a2, voffA);
;             PG8_WAIT_V(8); PG8_WAIT_L(0); PG8_BAR; PG8_MMA(1, 0, At, B0); PG8_MMA(1, 1, At, B1); PG8_BAR; PG8_SCHED;
.LBB0_403:
	s_add_u32 s52, s50, 0x100
	s_addc_u32 s53, s51, 0
	s_add_i32 s76, 0, 0x10000
	s_cmpk_eq_i32 s75, 0x54
	s_cselect_b32 s57, s45, s53
	s_cselect_b32 s56, s44, s52
	s_cselect_b32 s55, s47, s73
	s_cselect_b32 s54, s46, s72
	s_add_i32 s77, 0, 0x14000
	v_add_u32_e32 v146, s76, v233
	v_add_u32_e32 v162, s77, v233
	ds_read_b128 v[126:129], v146
	ds_read_b128 v[130:133], v146 offset:1024
	ds_read_b128 v[142:145], v146 offset:2048
	ds_read_b128 v[146:149], v146 offset:3072
	ds_read_b128 v[150:153], v162
	ds_read_b128 v[154:157], v162 offset:1024
	ds_read_b128 v[158:161], v162 offset:2048
	ds_read_b128 v[162:165], v162 offset:3072
	v_lshl_add_u64 v[210:211], s[50:51], 0, v[192:193]
	s_add_i32 m0, s60, 0xc000
	ds_read_b128 v[166:169], v236
	ds_read_b128 v[170:173], v236 offset:1024
	ds_read_b128 v[174:177], v236 offset:2048
	ds_read_b128 v[178:181], v236 offset:3072
	ds_read_b128 v[194:197], v236 offset:4096
	ds_read_b128 v[198:201], v236 offset:5120
	ds_read_b128 v[202:205], v236 offset:6144
	ds_read_b128 v[206:209], v236 offset:7168
	global_load_lds_dwordx4 v[210:211], off
	v_lshl_add_u64 v[210:211], s[50:51], 0, v[190:191]
	s_add_i32 m0, s60, 0xe000
	s_nop 0
	global_load_lds_dwordx4 v[210:211], off
	s_waitcnt vmcnt(8)
	s_waitcnt lgkmcnt(0)
	s_setprio 1
	v_mfma_f32_16x16x32_bf16 v[138:141], v[126:129], v[166:169], v[138:141]
	v_mfma_f32_16x16x32_bf16 v[134:137], v[142:145], v[166:169], v[134:137]
	v_mfma_f32_16x16x32_bf16 v[114:117], v[126:129], v[174:177], v[114:117]
	v_mfma_f32_16x16x32_bf16 v[110:113], v[142:145], v[174:177], v[110:113]
	s_barrier
	v_mfma_f32_16x16x32_bf16 v[92:95], v[126:129], v[194:197], v[92:95]
	v_mfma_f32_16x16x32_bf16 v[88:91], v[142:145], v[194:197], v[88:91]
	v_mfma_f32_16x16x32_bf16 v[76:79], v[126:129], v[202:205], v[76:79]
	v_mfma_f32_16x16x32_bf16 v[72:75], v[142:145], v[202:205], v[72:75]
	v_mfma_f32_16x16x32_bf16 v[138:141], v[130:133], v[170:173], v[138:141]
	v_mfma_f32_16x16x32_bf16 v[134:137], v[146:149], v[170:173], v[134:137]
	v_mfma_f32_16x16x32_bf16 v[114:117], v[130:133], v[178:181], v[114:117]
	v_mfma_f32_16x16x32_bf16 v[110:113], v[146:149], v[178:181], v[110:113]
	v_mfma_f32_16x16x32_bf16 v[92:95], v[130:133], v[198:201], v[92:95]
	v_mfma_f32_16x16x32_bf16 v[88:91], v[146:149], v[198:201], v[88:91]
	v_mfma_f32_16x16x32_bf16 v[76:79], v[130:133], v[206:209], v[76:79]
	v_mfma_f32_16x16x32_bf16 v[72:75], v[146:149], v[206:209], v[72:75]
	v_mfma_f32_16x16x32_bf16 v[122:125], v[150:153], v[166:169], v[122:125]
	v_mfma_f32_16x16x32_bf16 v[118:121], v[158:161], v[166:169], v[118:121]
	v_mfma_f32_16x16x32_bf16 v[106:109], v[150:153], v[174:177], v[106:109]
	v_mfma_f32_16x16x32_bf16 v[102:105], v[158:161], v[174:177], v[102:105]
	v_mfma_f32_16x16x32_bf16 v[84:87], v[150:153], v[194:197], v[84:87]
	v_mfma_f32_16x16x32_bf16 v[80:83], v[158:161], v[194:197], v[80:83]
	v_mfma_f32_16x16x32_bf16 v[68:71], v[150:153], v[202:205], v[68:71]
	v_mfma_f32_16x16x32_bf16 v[64:67], v[158:161], v[202:205], v[64:67]
	v_mfma_f32_16x16x32_bf16 v[122:125], v[154:157], v[170:173], v[122:125]
	v_mfma_f32_16x16x32_bf16 v[118:121], v[162:165], v[170:173], v[118:121]
	v_mfma_f32_16x16x32_bf16 v[106:109], v[154:157], v[178:181], v[106:109]
	v_mfma_f32_16x16x32_bf16 v[102:105], v[162:165], v[178:181], v[102:105]
	v_mfma_f32_16x16x32_bf16 v[84:87], v[154:157], v[198:201], v[84:87]
	v_mfma_f32_16x16x32_bf16 v[80:83], v[162:165], v[198:201], v[80:83]
	v_mfma_f32_16x16x32_bf16 v[68:71], v[154:157], v[206:209], v[68:71]
	v_mfma_f32_16x16x32_bf16 v[64:67], v[162:165], v[206:209], v[64:67]
	s_barrier
	s_setprio 0
	s_add_i32 s50, s76, s59
	v_lshl_add_u64 v[210:211], s[54:55], 0, v[96:97]
	s_mov_b32 m0, s50
	ds_read_b128 v[166:169], v236 offset:16384
	ds_read_b128 v[170:173], v236 offset:17408
	ds_read_b128 v[174:177], v236 offset:18432
	ds_read_b128 v[178:181], v236 offset:19456
	ds_read_b128 v[194:197], v236 offset:20480
	ds_read_b128 v[198:201], v236 offset:21504
	ds_read_b128 v[202:205], v236 offset:22528
	ds_read_b128 v[206:209], v236 offset:23552
	global_load_lds_dwordx4 v[210:211], off
	s_add_i32 m0, s50, 0x2000
	s_add_u32 s50, s54, 0x160000
	v_lshl_add_u64 v[212:213], s[54:55], 0, v[98:99]
	s_addc_u32 s51, s55, 0
	s_add_i32 s76, s77, s59
	global_load_lds_dwordx4 v[212:213], off
	v_lshl_add_u64 v[214:215], s[50:51], 0, v[96:97]
	s_mov_b32 m0, s76
	v_lshl_add_u64 v[216:217], s[56:57], 0, v[186:187]
	global_load_lds_dwordx4 v[214:215], off
	v_lshl_add_u64 v[214:215], s[50:51], 0, v[98:99]
	s_add_i32 m0, s76, 0x2000
	s_nop 0
	global_load_lds_dwordx4 v[214:215], off
	v_lshl_add_u64 v[214:215], s[56:57], 0, v[188:189]
	s_mov_b32 m0, s60
	s_nop 0
	global_load_lds_dwordx4 v[214:215], off
	s_mov_b32 m0, s61
	s_nop 0
	global_load_lds_dwordx4 v[216:217], off
	s_waitcnt vmcnt(8)
	s_waitcnt lgkmcnt(0)
	s_setprio 1
	v_mfma_f32_16x16x32_bf16 v[60:63], v[126:129], v[166:169], v[60:63]
	v_mfma_f32_16x16x32_bf16 v[56:59], v[142:145], v[166:169], v[56:59]
	v_mfma_f32_16x16x32_bf16 v[44:47], v[126:129], v[174:177], v[44:47]
	v_mfma_f32_16x16x32_bf16 v[40:43], v[142:145], v[174:177], v[40:43]
	s_barrier
; #define PG8_STAGE(bufoff, gbase, voff) do { _Pragma("unroll") for (int _i = 0; _i < 2; ++_i) \
;         __builtin_amdgcn_global_load_lds((const unsigned*)((const char*)(gbase) + (voff)[_i]), (PG8_LAS unsigned*)(lds + (bufoff) + ldsw + _i * 8192), 16, 0, 0); } while (0)
; #define PG8_LDA(dst, b, h) do { _Pragma("unroll") for (int m = 0; m < 4; ++m) _Pragma("unroll") for (int k = 0; k < 2; ++k) dst[m][k] = *(const PG8_LAS bf16x8*)(lds + PG8_SA(b, h) + aoff + m * 2048 + k * 1024); } while (0)
; #define PG8_LDB(dst, b, h) do { _Pragma("unroll") for (int n = 0; n < 2; ++n) _Pragma("unroll") for (int k = 0; k < 2; ++k) dst[n][k] = *(const PG8_LAS bf16x8*)(lds + PG8_SB(b, h) + boff + n * 2048 + k * 1024); } while (0)
; #define PG8_MMA(ai, bj, At, Bt) do { __builtin_amdgcn_s_setprio(1); _Pragma("unroll") for (int m = 0; m < 4; ++m) _Pragma("unroll") for (int n = 0; n < 2; ++n) _Pragma("unroll") for (int k = 0; k < 2; ++k) \
;         acc[ai][bj][m][n] = __builtin_amdgcn_mfma_f32_16x16x32_bf16(Bt[n][k], At[m][k], acc[ai][bj][m][n], 0, 0, 0); __builtin_amdgcn_s_setprio(0); } while (0)
; #define PG8_WAIT_V(n) asm volatile("s_waitcnt vmcnt(" #n ")" ::: "memory")
; #define PG8_WAIT_L(n) asm volatile("s_waitcnt lgkmcnt(" #n ")" ::: "memory")
; #define PG8_BAR __builtin_amdgcn_s_barrier()
; #define PG8_SCHED __builtin_amdgcn_sched_barrier(0)
; template <class Epi, class Sched, bool ALIGN_EPI = false, bool SP2 = false>
; __device__ __forceinline__ void gemm_phase(PG8_LAS unsigned char* lds, const Gemm g, const Sched& S, const Epi& E, const int tid) {
;     ...
;             PG8_WAIT_V(8); PG8_WAIT_L(0); PG8_BAR; PG8_MMA(1, 0, At, B0); PG8_MMA(1, 1, At, B1); PG8_BAR; PG8_SCHED;
;             PG8_LDB(B0, 1, 0); PG8_LDB(B1, 1, 1); PG8_SCHED; PG8_LDA(At, 1, 0); PG8_STAGE(PG8_SA(0, 1), a2 + hstep, voffA);
;             PG8_WAIT_V(8); PG8_WAIT_L(0); PG8_BAR; PG8_MMA(0, 0, At, B0); PG8_MMA(0, 1, At, B1); PG8_BAR; PG8_SCHED;
	v_mfma_f32_16x16x32_bf16 v[28:31], v[126:129], v[194:197], v[28:31]
	v_mfma_f32_16x16x32_bf16 v[24:27], v[142:145], v[194:197], v[24:27]
	v_mfma_f32_16x16x32_bf16 v[12:15], v[126:129], v[202:205], v[12:15]
	v_mfma_f32_16x16x32_bf16 v[8:11], v[142:145], v[202:205], v[8:11]
	v_mfma_f32_16x16x32_bf16 v[60:63], v[130:133], v[170:173], v[60:63]
	v_mfma_f32_16x16x32_bf16 v[56:59], v[146:149], v[170:173], v[56:59]
	v_mfma_f32_16x16x32_bf16 v[44:47], v[130:133], v[178:181], v[44:47]
	v_mfma_f32_16x16x32_bf16 v[40:43], v[146:149], v[178:181], v[40:43]
	v_mfma_f32_16x16x32_bf16 v[28:31], v[130:133], v[198:201], v[28:31]
	v_mfma_f32_16x16x32_bf16 v[24:27], v[146:149], v[198:201], v[24:27]
	v_mfma_f32_16x16x32_bf16 v[12:15], v[130:133], v[206:209], v[12:15]
	v_mfma_f32_16x16x32_bf16 v[8:11], v[146:149], v[206:209], v[8:11]
	v_mfma_f32_16x16x32_bf16 v[52:55], v[150:153], v[166:169], v[52:55]
	v_mfma_f32_16x16x32_bf16 v[48:51], v[158:161], v[166:169], v[48:51]
	v_mfma_f32_16x16x32_bf16 v[36:39], v[150:153], v[174:177], v[36:39]
	v_mfma_f32_16x16x32_bf16 v[32:35], v[158:161], v[174:177], v[32:35]
	v_mfma_f32_16x16x32_bf16 v[20:23], v[150:153], v[194:197], v[20:23]
	v_mfma_f32_16x16x32_bf16 v[16:19], v[158:161], v[194:197], v[16:19]
	v_mfma_f32_16x16x32_bf16 v[4:7], v[150:153], v[202:205], v[4:7]
	v_mfma_f32_16x16x32_bf16 v[0:3], v[158:161], v[202:205], v[0:3]
	v_mfma_f32_16x16x32_bf16 v[52:55], v[154:157], v[170:173], v[52:55]
	v_mfma_f32_16x16x32_bf16 v[48:51], v[162:165], v[170:173], v[48:51]
	v_mfma_f32_16x16x32_bf16 v[36:39], v[154:157], v[178:181], v[36:39]
	v_mfma_f32_16x16x32_bf16 v[32:35], v[162:165], v[178:181], v[32:35]
	v_mfma_f32_16x16x32_bf16 v[20:23], v[154:157], v[198:201], v[20:23]
	v_mfma_f32_16x16x32_bf16 v[16:19], v[162:165], v[198:201], v[16:19]
	v_mfma_f32_16x16x32_bf16 v[4:7], v[154:157], v[206:209], v[4:7]
	v_mfma_f32_16x16x32_bf16 v[0:3], v[162:165], v[206:209], v[0:3]
	s_barrier
	s_setprio 0
	s_add_i32 s76, 0, 0x18000
	s_add_i32 s77, 0, 0x1c000
	v_add_u32_e32 v146, s76, v233
	v_add_u32_e32 v162, s77, v233
	ds_read_b128 v[126:129], v146
	ds_read_b128 v[130:133], v146 offset:1024
	ds_read_b128 v[142:145], v146 offset:2048
	ds_read_b128 v[146:149], v146 offset:3072
	ds_read_b128 v[150:153], v162
	ds_read_b128 v[154:157], v162 offset:1024
	ds_read_b128 v[158:161], v162 offset:2048
	ds_read_b128 v[162:165], v162 offset:3072
	s_add_u32 s50, s56, 0x160000
	s_addc_u32 s51, s57, 0
	s_mov_b32 m0, s64
	v_lshl_add_u64 v[218:219], s[50:51], 0, v[188:189]
	ds_read_b128 v[166:169], v236 offset:32768
	ds_read_b128 v[170:173], v236 offset:33792
	ds_read_b128 v[174:177], v236 offset:34816
	ds_read_b128 v[178:181], v236 offset:35840
	ds_read_b128 v[194:197], v236 offset:36864
	ds_read_b128 v[198:201], v236 offset:37888
	ds_read_b128 v[202:205], v236 offset:38912
	ds_read_b128 v[206:209], v236 offset:39936
	global_load_lds_dwordx4 v[218:219], off
	v_lshl_add_u64 v[218:219], s[50:51], 0, v[186:187]
	s_mov_b32 m0, s65
	s_nop 0
	global_load_lds_dwordx4 v[218:219], off
	s_waitcnt vmcnt(8)
	s_waitcnt lgkmcnt(0)
	s_setprio 1
	v_mfma_f32_16x16x32_bf16 v[138:141], v[126:129], v[166:169], v[138:141]
	v_mfma_f32_16x16x32_bf16 v[134:137], v[142:145], v[166:169], v[134:137]
	v_mfma_f32_16x16x32_bf16 v[114:117], v[126:129], v[174:177], v[114:117]
	v_mfma_f32_16x16x32_bf16 v[110:113], v[142:145], v[174:177], v[110:113]
	s_barrier
	v_mfma_f32_16x16x32_bf16 v[92:95], v[126:129], v[194:197], v[92:95]
	v_mfma_f32_16x16x32_bf16 v[88:91], v[142:145], v[194:197], v[88:91]
	v_mfma_f32_16x16x32_bf16 v[76:79], v[126:129], v[202:205], v[76:79]
	v_mfma_f32_16x16x32_bf16 v[72:75], v[142:145], v[202:205], v[72:75]
	v_mfma_f32_16x16x32_bf16 v[138:141], v[130:133], v[170:173], v[138:141]
	v_mfma_f32_16x16x32_bf16 v[134:137], v[146:149], v[170:173], v[134:137]
	v_mfma_f32_16x16x32_bf16 v[114:117], v[130:133], v[178:181], v[114:117]
	v_mfma_f32_16x16x32_bf16 v[110:113], v[146:149], v[178:181], v[110:113]
	v_mfma_f32_16x16x32_bf16 v[92:95], v[130:133], v[198:201], v[92:95]
	v_mfma_f32_16x16x32_bf16 v[88:91], v[146:149], v[198:201], v[88:91]
	v_mfma_f32_16x16x32_bf16 v[76:79], v[130:133], v[206:209], v[76:79]
	v_mfma_f32_16x16x32_bf16 v[72:75], v[146:149], v[206:209], v[72:75]
	v_mfma_f32_16x16x32_bf16 v[122:125], v[150:153], v[166:169], v[122:125]
	v_mfma_f32_16x16x32_bf16 v[118:121], v[158:161], v[166:169], v[118:121]
	v_mfma_f32_16x16x32_bf16 v[106:109], v[150:153], v[174:177], v[106:109]
	v_mfma_f32_16x16x32_bf16 v[102:105], v[158:161], v[174:177], v[102:105]
	v_mfma_f32_16x16x32_bf16 v[84:87], v[150:153], v[194:197], v[84:87]
	v_mfma_f32_16x16x32_bf16 v[80:83], v[158:161], v[194:197], v[80:83]
	v_mfma_f32_16x16x32_bf16 v[68:71], v[150:153], v[202:205], v[68:71]
	v_mfma_f32_16x16x32_bf16 v[64:67], v[158:161], v[202:205], v[64:67]
	v_mfma_f32_16x16x32_bf16 v[122:125], v[154:157], v[170:173], v[122:125]
	v_mfma_f32_16x16x32_bf16 v[118:121], v[162:165], v[170:173], v[118:121]
	v_mfma_f32_16x16x32_bf16 v[106:109], v[154:157], v[178:181], v[106:109]
	v_mfma_f32_16x16x32_bf16 v[102:105], v[162:165], v[178:181], v[102:105]
	v_mfma_f32_16x16x32_bf16 v[84:87], v[154:157], v[198:201], v[84:87]
	v_mfma_f32_16x16x32_bf16 v[80:83], v[162:165], v[198:201], v[80:83]
	v_mfma_f32_16x16x32_bf16 v[68:71], v[154:157], v[206:209], v[68:71]
	v_mfma_f32_16x16x32_bf16 v[64:67], v[162:165], v[206:209], v[64:67]
	s_barrier
; #define PG8_GAS __attribute__((address_space(1)))
; #define PG8_STAGE(bufoff, gbase, voff) do { _Pragma("unroll") for (int _i = 0; _i < 2; ++_i) \
;         __builtin_amdgcn_global_load_lds((const unsigned*)((const char*)(gbase) + (voff)[_i]), (PG8_LAS unsigned*)(lds + (bufoff) + ldsw + _i * 8192), 16, 0, 0); } while (0)
; #define PG8_LDA(dst, b, h) do { _Pragma("unroll") for (int m = 0; m < 4; ++m) _Pragma("unroll") for (int k = 0; k < 2; ++k) dst[m][k] = *(const PG8_LAS bf16x8*)(lds + PG8_SA(b, h) + aoff + m * 2048 + k * 1024); } while (0)
; #define PG8_MMA(ai, bj, At, Bt) do { __builtin_amdgcn_s_setprio(1); _Pragma("unroll") for (int m = 0; m < 4; ++m) _Pragma("unroll") for (int n = 0; n < 2; ++n) _Pragma("unroll") for (int k = 0; k < 2; ++k) \
;         acc[ai][bj][m][n] = __builtin_amdgcn_mfma_f32_16x16x32_bf16(Bt[n][k], At[m][k], acc[ai][bj][m][n], 0, 0, 0); __builtin_amdgcn_s_setprio(0); } while (0)
; #define PG8_WAIT_V(n) asm volatile("s_waitcnt vmcnt(" #n ")" ::: "memory")
; #define PG8_WAIT_L(n) asm volatile("s_waitcnt lgkmcnt(" #n ")" ::: "memory")
; #define PG8_BAR __builtin_amdgcn_s_barrier()
;     __device__ __forceinline__ void operator()(const f32x4 (&acc)[2][2][4][2], const Unit& u, int wr, int wc, int fr, int fq) const {
;         const int row0 = u.pm * BM + wr * 64 + fr, col0 = u.pn * BM + wc * 32 + 8 * fq, lcol = u.pn * BM + (wc * 4 + fq) * 16;
; #pragma unroll
;         for (int ai = 0; ai < 2; ++ai) {
;             u32x4 L4[4], H4[4][2];
; #pragma unroll
;             for (int m = 0; m < 4; ++m) {
;                 const int row = row0 + ai * HALF + m * 16; const size_t off = (size_t)row * 2048 + col0, loff = (size_t)row * 2048 + lcol;
;                 L4[m] = *(const PG8_GAS u32x4*)(lin + loff); H4[m][0] = *(const PG8_GAS u32x4*)(hin + off); H4[m][1] = *(const PG8_GAS u32x4*)(hin + off + HALF);
;             }
; template <class Epi, class Sched, bool ALIGN_EPI = false, bool SP2 = false>
; __device__ __forceinline__ void gemm_phase(PG8_LAS unsigned char* lds, const Gemm g, const Sched& S, const Epi& E, const int tid) {
;     ...
;             PG8_LDA(At, 1, 1); PG8_STAGE(PG8_SB(1, 0), b3, voffB); PG8_STAGE(PG8_SB(1, 1), b3 + hstep, voffB); PG8_STAGE(PG8_SA(1, 0), a3, voffA);
;             PG8_WAIT_V(8); PG8_WAIT_L(0); PG8_BAR; PG8_MMA(1, 0, At, B0); PG8_MMA(1, 1, At, B1); PG8_BAR; PG8_SCHED;
	s_setprio 0
	s_add_i32 s50, s76, s59
	v_lshl_add_u64 v[210:211], v[210:211], 0, s[28:29]
	s_mov_b32 m0, s50
	ds_read_b128 v[166:169], v236 offset:49152
	ds_read_b128 v[170:173], v236 offset:50176
	ds_read_b128 v[174:177], v236 offset:51200
	ds_read_b128 v[178:181], v236 offset:52224
	ds_read_b128 v[194:197], v236 offset:53248
	ds_read_b128 v[198:201], v236 offset:54272
	ds_read_b128 v[202:205], v236 offset:55296
	ds_read_b128 v[206:209], v236 offset:56320
	global_load_lds_dwordx4 v[210:211], off
	s_add_i32 m0, s50, 0x2000
	s_add_u32 s50, s54, 0x160080
	v_lshl_add_u64 v[210:211], v[212:213], 0, s[28:29]
	s_addc_u32 s51, s55, 0
	s_add_i32 s54, s77, s59
	global_load_lds_dwordx4 v[210:211], off
	v_lshl_add_u64 v[210:211], s[50:51], 0, v[96:97]
	s_mov_b32 m0, s54
	s_nop 0
	global_load_lds_dwordx4 v[210:211], off
	v_lshl_add_u64 v[210:211], s[50:51], 0, v[98:99]
	s_add_i32 m0, s54, 0x2000
	s_nop 0
	global_load_lds_dwordx4 v[210:211], off
	v_lshl_add_u64 v[210:211], v[214:215], 0, s[28:29]
	s_mov_b32 m0, s63
	s_nop 0
	global_load_lds_dwordx4 v[210:211], off
	v_lshl_add_u64 v[210:211], v[216:217], 0, s[28:29]
	s_mov_b32 m0, s66
	s_nop 0
	global_load_lds_dwordx4 v[210:211], off
	s_waitcnt vmcnt(8)
	s_waitcnt lgkmcnt(0)
	s_setprio 1
	v_mfma_f32_16x16x32_bf16 v[60:63], v[126:129], v[166:169], v[60:63]
	v_mfma_f32_16x16x32_bf16 v[56:59], v[142:145], v[166:169], v[56:59]
	v_mfma_f32_16x16x32_bf16 v[44:47], v[126:129], v[174:177], v[44:47]
	v_mfma_f32_16x16x32_bf16 v[40:43], v[142:145], v[174:177], v[40:43]
	s_barrier
	v_mfma_f32_16x16x32_bf16 v[28:31], v[126:129], v[194:197], v[28:31]
	v_mfma_f32_16x16x32_bf16 v[24:27], v[142:145], v[194:197], v[24:27]
	v_mfma_f32_16x16x32_bf16 v[12:15], v[126:129], v[202:205], v[12:15]
	v_mfma_f32_16x16x32_bf16 v[8:11], v[142:145], v[202:205], v[8:11]
	v_mfma_f32_16x16x32_bf16 v[60:63], v[130:133], v[170:173], v[60:63]
	v_mfma_f32_16x16x32_bf16 v[56:59], v[146:149], v[170:173], v[56:59]
	v_mfma_f32_16x16x32_bf16 v[44:47], v[130:133], v[178:181], v[44:47]
	v_mfma_f32_16x16x32_bf16 v[40:43], v[146:149], v[178:181], v[40:43]
	v_mfma_f32_16x16x32_bf16 v[28:31], v[130:133], v[198:201], v[28:31]
	v_mfma_f32_16x16x32_bf16 v[24:27], v[146:149], v[198:201], v[24:27]
	v_mfma_f32_16x16x32_bf16 v[12:15], v[130:133], v[206:209], v[12:15]
	v_mfma_f32_16x16x32_bf16 v[8:11], v[146:149], v[206:209], v[8:11]
	v_mfma_f32_16x16x32_bf16 v[52:55], v[150:153], v[166:169], v[52:55]
	v_mfma_f32_16x16x32_bf16 v[48:51], v[158:161], v[166:169], v[48:51]
	v_mfma_f32_16x16x32_bf16 v[36:39], v[150:153], v[174:177], v[36:39]
	v_mfma_f32_16x16x32_bf16 v[32:35], v[158:161], v[174:177], v[32:35]
	v_mfma_f32_16x16x32_bf16 v[20:23], v[150:153], v[194:197], v[20:23]
	v_mfma_f32_16x16x32_bf16 v[16:19], v[158:161], v[194:197], v[16:19]
	v_mfma_f32_16x16x32_bf16 v[4:7], v[150:153], v[202:205], v[4:7]
	v_mfma_f32_16x16x32_bf16 v[0:3], v[158:161], v[202:205], v[0:3]
	v_mfma_f32_16x16x32_bf16 v[52:55], v[154:157], v[170:173], v[52:55]
	v_mfma_f32_16x16x32_bf16 v[48:51], v[162:165], v[170:173], v[48:51]
	v_mfma_f32_16x16x32_bf16 v[36:39], v[154:157], v[178:181], v[36:39]
	v_mfma_f32_16x16x32_bf16 v[32:35], v[162:165], v[178:181], v[32:35]
	v_mfma_f32_16x16x32_bf16 v[20:23], v[154:157], v[198:201], v[20:23]
	v_mfma_f32_16x16x32_bf16 v[16:19], v[162:165], v[198:201], v[16:19]
	v_mfma_f32_16x16x32_bf16 v[4:7], v[154:157], v[206:209], v[4:7]
	v_mfma_f32_16x16x32_bf16 v[0:3], v[162:165], v[206:209], v[0:3]
	s_barrier
	s_setprio 0
	s_add_i32 s75, s75, 2
	s_add_u32 s72, s72, 0x100
	s_addc_u32 s73, s73, 0
	s_cmpk_gt_u32 s75, 0x55
	s_mov_b64 s[50:51], s[52:53]
	s_cbranch_scc0 .LBB0_403
	v_and_b32_e32 v127, 64, v228
	v_xor_b32_e32 v126, 16, v228
	v_add_u32_e32 v127, 64, v127
	v_cmp_lt_i32_e32 vcc, v126, v127
	s_lshl_b32 s50, s70, 8
	v_lshl_add_u32 v198, s71, 8, v101
	v_cndmask_b32_e32 v126, v228, v126, vcc
	v_or_b32_e32 v194, s50, v235
	v_lshlrev_b32_e32 v238, 2, v126
	v_xor_b32_e32 v126, 32, v228
	v_or_b32_e32 v196, s50, v234
	v_ashrrev_i32_e32 v195, 31, v194
	v_cmp_lt_i32_e32 vcc, v126, v127
	v_ashrrev_i32_e32 v199, 31, v198
	v_ashrrev_i32_e32 v197, 31, v196
	v_cndmask_b32_e32 v126, v228, v126, vcc
	v_lshl_add_u64 v[202:203], s[34:35], 0, v[194:195]
	v_lshlrev_b64 v[216:217], 11, v[198:199]
	v_lshlrev_b32_e32 v237, 2, v126
	v_lshlrev_b64 v[218:219], 1, v[196:197]
	v_lshl_add_u64 v[126:127], v[202:203], 0, v[216:217]
	v_lshl_add_u64 v[200:201], s[30:31], 0, v[218:219]
	global_load_dwordx4 v[170:173], v[126:127], off
	v_lshlrev_b64 v[220:221], 12, v[198:199]
	v_lshl_add_u64 v[126:127], v[200:201], 0, v[220:221]
	global_load_dwordx4 v[178:181], v[126:127], off
	global_load_dwordx4 v[174:177], v[126:127], off offset:256
	v_or_b32_e32 v212, 16, v198
	v_ashrrev_i32_e32 v213, 31, v212
	v_lshlrev_b64 v[214:215], 11, v[212:213]
	v_lshl_add_u64 v[126:127], v[202:203], 0, v[214:215]
	v_or_b32_e32 v208, 32, v198
	global_load_dwordx4 v[158:161], v[126:127], off
	v_lshlrev_b64 v[126:127], 12, v[212:213]
	v_ashrrev_i32_e32 v209, 31, v208
	v_lshl_add_u64 v[126:127], v[200:201], 0, v[126:127]
	v_lshlrev_b64 v[210:211], 11, v[208:209]
	global_load_dwordx4 v[166:169], v[126:127], off
	global_load_dwordx4 v[162:165], v[126:127], off offset:256
	v_lshl_add_u64 v[126:127], v[202:203], 0, v[210:211]
	v_or_b32_e32 v204, 48, v198
	global_load_dwordx4 v[146:149], v[126:127], off
	v_lshlrev_b64 v[126:127], 12, v[208:209]
	v_ashrrev_i32_e32 v205, 31, v204
	v_lshl_add_u64 v[126:127], v[200:201], 0, v[126:127]
	v_lshlrev_b64 v[206:207], 11, v[204:205]
	v_lshlrev_b64 v[130:131], 12, v[204:205]
	global_load_dwordx4 v[154:157], v[126:127], off
	global_load_dwordx4 v[150:153], v[126:127], off offset:256
	v_lshl_add_u64 v[126:127], v[202:203], 0, v[206:207]
	v_lshl_add_u64 v[130:131], v[200:201], 0, v[130:131]
	global_load_dwordx4 v[126:129], v[126:127], off
	s_nop 0
	global_load_dwordx4 v[142:145], v[130:131], off
	s_nop 0
	global_load_dwordx4 v[130:133], v[130:131], off offset:256
	v_mov_b32_e32 v243, v136
	v_mov_b32_e32 v242, v140
	s_waitcnt vmcnt(0)
; #define PG8_GAS __attribute__((address_space(1)))
; __device__ __forceinline__ float e_x24(unsigned h16, unsigned l8) { return __uint_as_float(((h16 - (l8 >> 7)) << 16) | (l8 << 8)); }
;     __device__ __forceinline__ void operator()(const f32x4 (&acc)[2][2][4][2], const Unit& u, int wr, int wc, int fr, int fq) const {
;     ...
;             for (int m = 0; m < 4; ++m) {
;                 const int row = row0 + ai * HALF + m * 16; const size_t off = (size_t)row * 2048 + col0, loff = (size_t)row * 2048 + lcol; float ss = 0.f;
;                 const u32x4 l4 = L4[m];
;                 u32x4 lo4;
; #pragma unroll
;                 for (int bj = 0; bj < 2; ++bj) {
;                     const u32x4 h4 = H4[m][bj];
;                     u32x4 ho;
; #pragma unroll
;                     for (int j = 0; j < 4; ++j) {
;                         const unsigned lw = l4[2 * bj + (j >> 1)], lb0 = (lw >> (16 * (j & 1))) & 0xffu, lb1 = (lw >> (16 * (j & 1) + 8)) & 0xffu;
;                         const float x0 = e_x24(h4[j] & 0xffffu, lb0) + acc[ai][bj][m][j >> 1][2 * (j & 1)] * scale, x1 = e_x24(h4[j] >> 16, lb1) + acc[ai][bj][m][j >> 1][2 * (j & 1) + 1] * scale;
;                         const unsigned b0 = __float_as_uint(x0), b1 = __float_as_uint(x1);
;                         ho[j] = ((b0 + 0x8000u) >> 16) | ((b1 + 0x8000u) & 0xffff0000u);
;                         const unsigned nb = ((b0 >> 8) & 0xffu) | (b1 & 0xff00u);
;                         if ((j & 1) == 0) lo4[2 * bj + (j >> 1)] = nb; else lo4[2 * bj + (j >> 1)] |= nb << 16;
;                         ss += x0 * x0 + x1 * x1;
;                     }
;                     *(PG8_GAS u32x4*)(hout + off + bj * HALF) = ho;
;                 }
	v_lshrrev_b32_sdwa v222, v229, v171 dst_sel:DWORD dst_unused:UNUSED_PAD src0_sel:DWORD src1_sel:BYTE_0
	v_lshrrev_b32_sdwa v223, v229, v170 dst_sel:DWORD dst_unused:UNUSED_PAD src0_sel:DWORD src1_sel:BYTE_0
	v_sub_u32_sdwa v224, v178, v223 dst_sel:WORD_1 dst_unused:UNUSED_PAD src0_sel:DWORD src1_sel:DWORD
	v_sub_u32_sdwa v222, v180, v222 dst_sel:WORD_1 dst_unused:UNUSED_PAD src0_sel:DWORD src1_sel:DWORD
	v_lshlrev_b32_sdwa v223, v230, v171 dst_sel:DWORD dst_unused:UNUSED_PAD src0_sel:DWORD src1_sel:BYTE_0
	v_lshlrev_b32_sdwa v225, v230, v170 dst_sel:DWORD dst_unused:UNUSED_PAD src0_sel:DWORD src1_sel:BYTE_0
	v_or_b32_e32 v223, v222, v223
	v_or_b32_e32 v222, v224, v225
	v_mov_b32_e32 v224, v138
	v_mov_b32_e32 v225, v134
	v_pk_fma_f32 v[222:223], v[224:225], 0.5, v[222:223] op_sel_hi:[1,0,1]
	v_lshlrev_b32_e32 v224, 1, v170
	v_add_u32_e32 v134, 0x8000, v222
	v_lshrrev_b32_e32 v138, 16, v134
	v_lshlrev_b32_e32 v134, 1, v171
	v_and_b32_e32 v134, 0x10000, v134
	v_and_b32_e32 v224, 0x10000, v224
	v_sub_u32_e32 v134, v180, v134
	v_sub_u32_e32 v178, v178, v224
	v_and_b32_e32 v134, 0xffff0000, v134
	v_and_b32_e32 v178, 0xffff0000, v178
	v_and_b32_e32 v180, 0xff00, v171
	v_and_b32_e32 v224, 0xff00, v170
	v_or_b32_e32 v225, v134, v180
	v_or_b32_e32 v224, v178, v224
	v_mov_b32_e32 v134, v139
	v_pk_fma_f32 v[224:225], v[134:135], 0.5, v[224:225] op_sel_hi:[1,0,1]
	v_and_b32_sdwa v135, v171, s93 dst_sel:DWORD dst_unused:UNUSED_PAD src0_sel:WORD_1 src1_sel:DWORD
	v_and_b32_sdwa v178, v170, s93 dst_sel:DWORD dst_unused:UNUSED_PAD src0_sel:WORD_1 src1_sel:DWORD
	v_lshlrev_b32_sdwa v239, v231, v170 dst_sel:DWORD dst_unused:UNUSED_PAD src0_sel:DWORD src1_sel:BYTE_3
	v_lshlrev_b32_sdwa v136, v231, v171 dst_sel:DWORD dst_unused:UNUSED_PAD src0_sel:DWORD src1_sel:BYTE_3
	v_lshrrev_b32_e32 v180, 7, v178
	v_lshrrev_b32_e32 v240, 7, v135
	v_and_b32_e32 v136, 0x10000, v136
	v_and_b32_e32 v140, 0x10000, v239
	v_sub_u32_sdwa v180, v179, v180 dst_sel:WORD_1 dst_unused:UNUSED_PAD src0_sel:DWORD src1_sel:DWORD
	v_sub_u32_sdwa v240, v181, v240 dst_sel:WORD_1 dst_unused:UNUSED_PAD src0_sel:DWORD src1_sel:DWORD
	v_lshlrev_b32_e32 v135, 8, v135
	v_lshlrev_b32_e32 v178, 8, v178
	v_sub_u32_e32 v136, v181, v136
	v_sub_u32_e32 v140, v179, v140
	v_or_b32_e32 v241, v240, v135
	v_or_b32_e32 v240, v180, v178
	v_and_b32_e32 v136, 0xffff0000, v136
	v_and_b32_e32 v140, 0xffff0000, v140
	v_lshlrev_b32_sdwa v171, v230, v171 dst_sel:DWORD dst_unused:UNUSED_PAD src0_sel:DWORD src1_sel:BYTE_3
	v_lshlrev_b32_sdwa v170, v230, v170 dst_sel:DWORD dst_unused:UNUSED_PAD src0_sel:DWORD src1_sel:BYTE_3
	v_pk_fma_f32 v[240:241], v[242:243], 0.5, v[240:241] op_sel_hi:[1,0,1]
	v_or_b32_e32 v171, v136, v171
	v_or_b32_e32 v170, v140, v170
	v_mov_b32_e32 v136, v141
	v_add_u32_e32 v135, 0x8000, v240
	v_pk_fma_f32 v[140:141], v[136:137], 0.5, v[170:171] op_sel_hi:[1,0,1]
	v_lshrrev_b32_e32 v135, 16, v135
	v_add_u32_e32 v136, 0x8000, v140
	v_and_or_b32 v135, v136, s90, v135
	v_pk_mul_f32 v[136:137], v[140:141], v[140:141]
	v_add_u32_e32 v178, 0x8000, v141
	v_pk_fma_f32 v[170:171], v[240:241], v[240:241], v[136:137]
	v_add_u32_e32 v136, 0x8000, v223
	v_lshrrev_b32_e32 v136, 16, v136
	v_add_u32_e32 v137, 0x8000, v225
	v_and_or_b32 v136, v137, s90, v136
	v_add_u32_e32 v137, 0x8000, v241
	v_lshrrev_b32_e32 v137, 16, v137
	v_add_u32_e32 v134, 0x8000, v224
	v_and_or_b32 v137, v178, s90, v137
	v_lshl_add_u64 v[178:179], s[30:31], 0, v[220:221]
	v_and_or_b32 v134, v134, s90, v138
	v_lshl_add_u64 v[178:179], v[178:179], 0, v[218:219]
	global_store_dwordx4 v[178:179], v[134:137], off
	v_lshlrev_b32_sdwa v220, v231, v172 dst_sel:DWORD dst_unused:UNUSED_PAD src0_sel:DWORD src1_sel:BYTE_3
	v_mov_b32_e32 v219, v120
	v_lshrrev_b32_sdwa v134, v229, v173 dst_sel:DWORD dst_unused:UNUSED_PAD src0_sel:DWORD src1_sel:BYTE_0
	v_lshrrev_b32_sdwa v135, v229, v172 dst_sel:DWORD dst_unused:UNUSED_PAD src0_sel:DWORD src1_sel:BYTE_0
	v_sub_u32_sdwa v136, v174, v135 dst_sel:WORD_1 dst_unused:UNUSED_PAD src0_sel:DWORD src1_sel:DWORD
	v_sub_u32_sdwa v134, v176, v134 dst_sel:WORD_1 dst_unused:UNUSED_PAD src0_sel:DWORD src1_sel:DWORD
	v_lshlrev_b32_sdwa v135, v230, v173 dst_sel:DWORD dst_unused:UNUSED_PAD src0_sel:DWORD src1_sel:BYTE_0
	v_lshlrev_b32_sdwa v137, v230, v172 dst_sel:DWORD dst_unused:UNUSED_PAD src0_sel:DWORD src1_sel:BYTE_0
	v_or_b32_e32 v135, v134, v135
	v_or_b32_e32 v134, v136, v137
	v_mov_b32_e32 v136, v122
	v_mov_b32_e32 v137, v118
	v_pk_fma_f32 v[134:135], v[136:137], 0.5, v[134:135] op_sel_hi:[1,0,1]
; #define PG8_GAS __attribute__((address_space(1)))
; __device__ __forceinline__ float e_x24(unsigned h16, unsigned l8) { return __uint_as_float(((h16 - (l8 >> 7)) << 16) | (l8 << 8)); }
;     __device__ __forceinline__ void operator()(const f32x4 (&acc)[2][2][4][2], const Unit& u, int wr, int wc, int fr, int fq) const {
;     ...
;                         const float x0 = e_x24(h4[j] & 0xffffu, lb0) + acc[ai][bj][m][j >> 1][2 * (j & 1)] * scale, x1 = e_x24(h4[j] >> 16, lb1) + acc[ai][bj][m][j >> 1][2 * (j & 1) + 1] * scale;
;                         const unsigned b0 = __float_as_uint(x0), b1 = __float_as_uint(x1);
;                         ho[j] = ((b0 + 0x8000u) >> 16) | ((b1 + 0x8000u) & 0xffff0000u);
;                         const unsigned nb = ((b0 >> 8) & 0xffu) | (b1 & 0xff00u);
;                         if ((j & 1) == 0) lo4[2 * bj + (j >> 1)] = nb; else lo4[2 * bj + (j >> 1)] |= nb << 16;
;                         ss += x0 * x0 + x1 * x1;
;                     }
;                     *(PG8_GAS u32x4*)(hout + off + bj * HALF) = ho;
;                 }
;                 *(PG8_GAS u32x4*)(lout + loff) = lo4;
;                 ss += __shfl_xor(ss, 16); ss += __shfl_xor(ss, 32);
;                 if (fq == 0) __hip_atomic_fetch_add((PG8_GAS unsigned long long*)(rowsq_out + row), (unsigned long long)(ss * 16777216.0f + 0.5f), __ATOMIC_RELAXED, __HIP_MEMORY_SCOPE_AGENT);
	v_lshlrev_b32_e32 v122, 1, v172
	v_add_u32_e32 v118, 0x8000, v134
	v_lshrrev_b32_e32 v180, 16, v118
	v_lshlrev_b32_e32 v118, 1, v173
	v_and_b32_e32 v118, 0x10000, v118
	v_and_b32_e32 v122, 0x10000, v122
	v_sub_u32_e32 v118, v176, v118
	v_sub_u32_e32 v122, v174, v122
	v_and_b32_e32 v118, 0xffff0000, v118
	v_and_b32_e32 v122, 0xffff0000, v122
	v_and_b32_e32 v136, 0xff00, v173
	v_and_b32_e32 v174, 0xff00, v172
	v_or_b32_e32 v137, v118, v136
	v_or_b32_e32 v136, v122, v174
	v_mov_b32_e32 v118, v123
	v_pk_fma_f32 v[122:123], v[118:119], 0.5, v[136:137] op_sel_hi:[1,0,1]
	v_and_b32_sdwa v119, v173, s93 dst_sel:DWORD dst_unused:UNUSED_PAD src0_sel:WORD_1 src1_sel:DWORD
	v_add_u32_e32 v118, 0x8000, v122
	v_and_b32_sdwa v174, v172, s93 dst_sel:DWORD dst_unused:UNUSED_PAD src0_sel:WORD_1 src1_sel:DWORD
	v_lshlrev_b32_sdwa v120, v231, v173 dst_sel:DWORD dst_unused:UNUSED_PAD src0_sel:DWORD src1_sel:BYTE_3
	v_and_or_b32 v118, v118, s90, v180
	v_lshrrev_b32_e32 v176, 7, v174
	v_lshrrev_b32_e32 v180, 7, v119
	v_mov_b32_e32 v218, v124
	v_and_b32_e32 v120, 0x10000, v120
	v_and_b32_e32 v124, 0x10000, v220
	v_sub_u32_sdwa v176, v175, v176 dst_sel:WORD_1 dst_unused:UNUSED_PAD src0_sel:DWORD src1_sel:DWORD
	v_sub_u32_sdwa v180, v177, v180 dst_sel:WORD_1 dst_unused:UNUSED_PAD src0_sel:DWORD src1_sel:DWORD
	v_lshlrev_b32_e32 v119, 8, v119
	v_lshlrev_b32_e32 v174, 8, v174
	v_sub_u32_e32 v120, v177, v120
	v_sub_u32_e32 v124, v175, v124
	v_or_b32_e32 v181, v180, v119
	v_or_b32_e32 v180, v176, v174
	v_and_b32_e32 v120, 0xffff0000, v120
	v_and_b32_e32 v124, 0xffff0000, v124
	v_lshlrev_b32_sdwa v173, v230, v173 dst_sel:DWORD dst_unused:UNUSED_PAD src0_sel:DWORD src1_sel:BYTE_3
	v_lshlrev_b32_sdwa v172, v230, v172 dst_sel:DWORD dst_unused:UNUSED_PAD src0_sel:DWORD src1_sel:BYTE_3
	v_pk_fma_f32 v[180:181], v[218:219], 0.5, v[180:181] op_sel_hi:[1,0,1]
	v_or_b32_e32 v173, v120, v173
	v_or_b32_e32 v172, v124, v172
	v_mov_b32_e32 v120, v125
	v_add_u32_e32 v119, 0x8000, v180
	v_pk_fma_f32 v[124:125], v[120:121], 0.5, v[172:173] op_sel_hi:[1,0,1]
	v_lshrrev_b32_e32 v119, 16, v119
	v_add_u32_e32 v120, 0x8000, v124
	v_pk_mul_f32 v[138:139], v[224:225], v[224:225]
	v_pk_mul_f32 v[136:137], v[122:123], v[122:123]
	v_and_or_b32 v119, v120, s90, v119
	v_pk_mul_f32 v[120:121], v[124:125], v[124:125]
	v_pk_fma_f32 v[138:139], v[222:223], v[222:223], v[138:139]
	v_pk_fma_f32 v[136:137], v[134:135], v[134:135], v[136:137]
	v_pk_fma_f32 v[172:173], v[180:181], v[180:181], v[120:121]
	v_add_u32_e32 v120, 0x8000, v135
	v_lshrrev_b32_e32 v134, 8, v134
	v_lshrrev_b32_e32 v120, 16, v120
	v_add_u32_e32 v121, 0x8000, v123
	v_perm_b32 v122, v122, v134, s94
	v_add_f32_e32 v134, v138, v170
	v_and_or_b32 v120, v121, s90, v120
	v_add_u32_e32 v121, 0x8000, v181
	v_add_f32_e32 v134, v139, v134
	v_lshrrev_b32_e32 v121, 16, v121
	v_add_u32_e32 v174, 0x8000, v125
	v_add_f32_e32 v134, v171, v134
	v_and_or_b32 v121, v174, s90, v121
	v_lshrrev_b32_e32 v174, 8, v181
	v_lshrrev_b32_e32 v175, 8, v180
	v_add_f32_e32 v134, v136, v134
	v_lshrrev_b32_e32 v176, 8, v241
	v_lshrrev_b32_e32 v177, 8, v240
	v_perm_b32 v124, v124, v175, s94
	v_perm_b32 v125, v125, v174, s94
	v_lshrrev_b32_e32 v135, 8, v135
	v_lshrrev_b32_e32 v174, 8, v223
	v_lshrrev_b32_e32 v175, 8, v222
	v_add_f32_e32 v134, v172, v134
	v_perm_b32 v140, v140, v177, s94
	v_perm_b32 v141, v141, v176, s94
	v_perm_b32 v175, v224, v175, s94
	v_perm_b32 v174, v225, v174, s94
	v_perm_b32 v123, v123, v135, s94
	v_add_f32_e32 v134, v137, v134
	global_store_dwordx4 v[178:179], v[118:121], off offset:256
	v_lshl_or_b32 v125, v125, 16, v123
	v_lshl_or_b32 v124, v124, 16, v122
	v_lshl_add_u64 v[118:119], s[34:35], 0, v[216:217]
	v_lshl_or_b32 v123, v141, 16, v174
	v_lshl_or_b32 v122, v140, 16, v175
	v_add_f32_e32 v134, v173, v134
	v_lshl_add_u64 v[118:119], v[118:119], 0, v[194:195]
	global_store_dwordx4 v[118:119], v[122:125], off
	ds_bpermute_b32 v118, v238, v134
	s_waitcnt lgkmcnt(0)
	v_add_f32_e32 v118, v134, v118
	ds_bpermute_b32 v119, v237, v118
	s_and_saveexec_b64 s[50:51], s[40:41]
	s_cbranch_execz .LBB0_406
	s_waitcnt lgkmcnt(0)
	v_add_f32_e32 v118, v118, v119
	v_fma_f32 v118, v118, s80, 0.5
	v_trunc_f32_e32 v118, v118
	v_mul_f32_e32 v119, 0x2f800000, v118
	v_floor_f32_e32 v119, v119
	v_fmac_f32_e32 v118, 0xcf800000, v119
	v_cvt_u32_f32_e32 v118, v118
	v_cvt_u32_f32_e32 v119, v119
	v_lshl_add_u64 v[120:121], v[198:199], 3, s[48:49]
	global_atomic_add_x2 v[120:121], v[118:119], off

; #define PG8_STAGE(bufoff, gbase, voff) do { _Pragma("unroll") for (int _i = 0; _i < 2; ++_i) \
;         __builtin_amdgcn_global_load_lds((const unsigned*)((const char*)(gbase) + (voff)[_i]), (PG8_LAS unsigned*)(lds + (bufoff) + ldsw + _i * 8192), 16, 0, 0); } while (0)
; #define PG8_LDA(dst, b, h) do { _Pragma("unroll") for (int m = 0; m < 4; ++m) _Pragma("unroll") for (int k = 0; k < 2; ++k) dst[m][k] = *(const PG8_LAS bf16x8*)(lds + PG8_SA(b, h) + aoff + m * 2048 + k * 1024); } while (0)
; #define PG8_LDB(dst, b, h) do { _Pragma("unroll") for (int n = 0; n < 2; ++n) _Pragma("unroll") for (int k = 0; k < 2; ++k) dst[n][k] = *(const PG8_LAS bf16x8*)(lds + PG8_SB(b, h) + boff + n * 2048 + k * 1024); } while (0)
; #define PG8_MMA(ai, bj, At, Bt) do { __builtin_amdgcn_s_setprio(1); _Pragma("unroll") for (int m = 0; m < 4; ++m) _Pragma("unroll") for (int n = 0; n < 2; ++n) _Pragma("unroll") for (int k = 0; k < 2; ++k) \
;         acc[ai][bj][m][n] = __builtin_amdgcn_mfma_f32_16x16x32_bf16(Bt[n][k], At[m][k], acc[ai][bj][m][n], 0, 0, 0); __builtin_amdgcn_s_setprio(0); } while (0)
; #define PG8_WAIT_V(n) asm volatile("s_waitcnt vmcnt(" #n ")" ::: "memory")
; #define PG8_WAIT_L(n) asm volatile("s_waitcnt lgkmcnt(" #n ")" ::: "memory")
; template <class Epi, class Sched, bool ALIGN_EPI = false, bool SP2 = false>
; __device__ __forceinline__ void gemm_phase(PG8_LAS unsigned char* lds, const Gemm g, const Sched& S, const Epi& E, const int tid) {
;     ...
;             const bool last = (t == nt - 2);
;             const char* a1 = cA + (size_t)(t + 1) * kstep;
;             const char* a2 = last ? nA : cA + (size_t)(t + 2) * kstep; const char* b2 = last ? nB : cB + (size_t)(t + 2) * kstep;
;             const char* a3 = a2 + kstep; const char* b3 = b2 + kstep;
;             if (last && has_next) S.a_ready(nxt);
;             if constexpr (SP2) {
;             PG8_LDB(B0, 0, 0); PG8_LDB(B1, 0, 1); PG8_SCHED; PG8_LDA(At, 0, 0); PG8_STAGE(PG8_SA(1, 1), a1 + hstep, voffA);
;             PG8_WAIT_V(8); PG8_WAIT_L(0); PG8_BAR; PG8_MMA(0, 0, At, B0); PG8_MMA(0, 1, At, B1); PG8_BAR; PG8_SCHED;
;             PG8_LDA(At, 0, 1); PG8_STAGE(PG8_SB(0, 0), b2, voffB); PG8_STAGE(PG8_SB(0, 1), b2 + hstep, voffB); PG8_STAGE(PG8_SA(0, 0), a2, voffA);
;             PG8_WAIT_V(8); PG8_WAIT_L(0); PG8_BAR; PG8_MMA(1, 0, At, B0); PG8_MMA(1, 1, At, B1); PG8_BAR; PG8_SCHED;
.LBB0_488:
	s_add_u32 s58, s42, 0xfff80080
	s_addc_u32 s59, s43, -1
	s_add_i32 s78, 0, 0x10000
	s_cmp_eq_u32 s77, 28
	s_cselect_b32 s61, s53, s59
	s_cselect_b32 s60, s72, s58
	s_cselect_b32 s59, s51, s76
	s_cselect_b32 s58, s73, s75
	s_add_i32 s80, 0, 0x14000
	v_add_u32_e32 v156, s78, v163
	v_add_u32_e32 v160, s80, v163
	ds_read_b128 v[144:147], v156
	ds_read_b128 v[148:151], v156 offset:1024
	ds_read_b128 v[152:155], v156 offset:2048
	ds_read_b128 v[156:159], v156 offset:3072
	ds_read_b128 v[166:169], v160
	ds_read_b128 v[170:173], v160 offset:1024
	ds_read_b128 v[174:177], v160 offset:2048
	ds_read_b128 v[178:181], v160 offset:3072
	v_lshl_add_u64 v[160:161], s[42:43], 0, v[142:143]
	s_add_i32 m0, s63, 0xc000
	ds_read_b128 v[186:189], v165
	ds_read_b128 v[190:193], v165 offset:1024
	ds_read_b128 v[194:197], v165 offset:2048
	ds_read_b128 v[198:201], v165 offset:3072
	ds_read_b128 v[202:205], v165 offset:4096
	ds_read_b128 v[206:209], v165 offset:5120
	ds_read_b128 v[210:213], v165 offset:6144
	ds_read_b128 v[214:217], v165 offset:7168
	global_load_lds_dwordx4 v[160:161], off
	v_lshl_add_u64 v[160:161], s[42:43], 0, v[140:141]
	s_add_i32 m0, s63, 0xe000
	s_nop 0
	global_load_lds_dwordx4 v[160:161], off
	s_waitcnt vmcnt(8)
	s_waitcnt lgkmcnt(0)
	s_setprio 1
	v_mfma_f32_16x16x32_bf16 v[122:125], v[144:147], v[186:189], v[122:125]
	v_mfma_f32_16x16x32_bf16 v[118:121], v[152:155], v[186:189], v[118:121]
	v_mfma_f32_16x16x32_bf16 v[110:113], v[144:147], v[194:197], v[110:113]
	v_mfma_f32_16x16x32_bf16 v[106:109], v[152:155], v[194:197], v[106:109]
	s_barrier
	v_mfma_f32_16x16x32_bf16 v[88:91], v[144:147], v[202:205], v[88:91]
	v_mfma_f32_16x16x32_bf16 v[84:87], v[152:155], v[202:205], v[84:87]
	v_mfma_f32_16x16x32_bf16 v[72:75], v[144:147], v[210:213], v[72:75]
	v_mfma_f32_16x16x32_bf16 v[68:71], v[152:155], v[210:213], v[68:71]
	v_mfma_f32_16x16x32_bf16 v[122:125], v[148:151], v[190:193], v[122:125]
	v_mfma_f32_16x16x32_bf16 v[118:121], v[156:159], v[190:193], v[118:121]
	v_mfma_f32_16x16x32_bf16 v[110:113], v[148:151], v[198:201], v[110:113]
	v_mfma_f32_16x16x32_bf16 v[106:109], v[156:159], v[198:201], v[106:109]
	v_mfma_f32_16x16x32_bf16 v[88:91], v[148:151], v[206:209], v[88:91]
	v_mfma_f32_16x16x32_bf16 v[84:87], v[156:159], v[206:209], v[84:87]
	v_mfma_f32_16x16x32_bf16 v[72:75], v[148:151], v[214:217], v[72:75]
	v_mfma_f32_16x16x32_bf16 v[68:71], v[156:159], v[214:217], v[68:71]
	v_mfma_f32_16x16x32_bf16 v[130:133], v[166:169], v[186:189], v[130:133]
	v_mfma_f32_16x16x32_bf16 v[126:129], v[174:177], v[186:189], v[126:129]
	v_mfma_f32_16x16x32_bf16 v[114:117], v[166:169], v[194:197], v[114:117]
	v_mfma_f32_16x16x32_bf16 v[102:105], v[174:177], v[194:197], v[102:105]
	v_mfma_f32_16x16x32_bf16 v[92:95], v[166:169], v[202:205], v[92:95]
	v_mfma_f32_16x16x32_bf16 v[80:83], v[174:177], v[202:205], v[80:83]
	v_mfma_f32_16x16x32_bf16 v[76:79], v[166:169], v[210:213], v[76:79]
	v_mfma_f32_16x16x32_bf16 v[64:67], v[174:177], v[210:213], v[64:67]
	v_mfma_f32_16x16x32_bf16 v[130:133], v[170:173], v[190:193], v[130:133]
	v_mfma_f32_16x16x32_bf16 v[126:129], v[178:181], v[190:193], v[126:129]
	v_mfma_f32_16x16x32_bf16 v[114:117], v[170:173], v[198:201], v[114:117]
	v_mfma_f32_16x16x32_bf16 v[102:105], v[178:181], v[198:201], v[102:105]
	v_mfma_f32_16x16x32_bf16 v[92:95], v[170:173], v[206:209], v[92:95]
	v_mfma_f32_16x16x32_bf16 v[80:83], v[178:181], v[206:209], v[80:83]
	v_mfma_f32_16x16x32_bf16 v[76:79], v[170:173], v[214:217], v[76:79]
	v_mfma_f32_16x16x32_bf16 v[64:67], v[178:181], v[214:217], v[64:67]
	s_barrier
	s_setprio 0
	s_add_i32 s78, s78, s62
	v_lshl_add_u64 v[160:161], s[58:59], 0, v[96:97]
	s_mov_b32 m0, s78
	ds_read_b128 v[186:189], v165 offset:16384
	ds_read_b128 v[190:193], v165 offset:17408
	ds_read_b128 v[194:197], v165 offset:18432
	ds_read_b128 v[198:201], v165 offset:19456
	ds_read_b128 v[202:205], v165 offset:20480
	ds_read_b128 v[206:209], v165 offset:21504
	ds_read_b128 v[210:213], v165 offset:22528
	ds_read_b128 v[214:217], v165 offset:23552
	global_load_lds_dwordx4 v[160:161], off
	s_add_i32 m0, s78, 0x2000
	s_add_u32 s78, s58, 0x80000
	v_lshl_add_u64 v[218:219], s[58:59], 0, v[98:99]
	s_addc_u32 s79, s59, 0
	s_add_i32 s80, s80, s62
	global_load_lds_dwordx4 v[218:219], off
	v_lshl_add_u64 v[220:221], s[78:79], 0, v[96:97]
	s_mov_b32 m0, s80
	v_lshl_add_u64 v[222:223], s[60:61], 0, v[134:135]
	global_load_lds_dwordx4 v[220:221], off
	v_lshl_add_u64 v[220:221], s[78:79], 0, v[98:99]
	s_add_i32 m0, s80, 0x2000
	s_nop 0
	global_load_lds_dwordx4 v[220:221], off
	v_lshl_add_u64 v[220:221], s[60:61], 0, v[136:137]
	s_mov_b32 m0, s63
	s_nop 0
	global_load_lds_dwordx4 v[220:221], off
	s_mov_b32 m0, s64
	s_nop 0
	global_load_lds_dwordx4 v[222:223], off
	s_waitcnt vmcnt(8)
	s_waitcnt lgkmcnt(0)
	s_setprio 1
	v_mfma_f32_16x16x32_bf16 v[56:59], v[144:147], v[186:189], v[56:59]
	v_mfma_f32_16x16x32_bf16 v[52:55], v[152:155], v[186:189], v[52:55]
	v_mfma_f32_16x16x32_bf16 v[40:43], v[144:147], v[194:197], v[40:43]
	v_mfma_f32_16x16x32_bf16 v[36:39], v[152:155], v[194:197], v[36:39]
	s_barrier
; #define PG8_STAGE(bufoff, gbase, voff) do { _Pragma("unroll") for (int _i = 0; _i < 2; ++_i) \
;         __builtin_amdgcn_global_load_lds((const unsigned*)((const char*)(gbase) + (voff)[_i]), (PG8_LAS unsigned*)(lds + (bufoff) + ldsw + _i * 8192), 16, 0, 0); } while (0)
; #define PG8_LDA(dst, b, h) do { _Pragma("unroll") for (int m = 0; m < 4; ++m) _Pragma("unroll") for (int k = 0; k < 2; ++k) dst[m][k] = *(const PG8_LAS bf16x8*)(lds + PG8_SA(b, h) + aoff + m * 2048 + k * 1024); } while (0)
; #define PG8_LDB(dst, b, h) do { _Pragma("unroll") for (int n = 0; n < 2; ++n) _Pragma("unroll") for (int k = 0; k < 2; ++k) dst[n][k] = *(const PG8_LAS bf16x8*)(lds + PG8_SB(b, h) + boff + n * 2048 + k * 1024); } while (0)
; #define PG8_MMA(ai, bj, At, Bt) do { __builtin_amdgcn_s_setprio(1); _Pragma("unroll") for (int m = 0; m < 4; ++m) _Pragma("unroll") for (int n = 0; n < 2; ++n) _Pragma("unroll") for (int k = 0; k < 2; ++k) \
;         acc[ai][bj][m][n] = __builtin_amdgcn_mfma_f32_16x16x32_bf16(Bt[n][k], At[m][k], acc[ai][bj][m][n], 0, 0, 0); __builtin_amdgcn_s_setprio(0); } while (0)
; #define PG8_WAIT_V(n) asm volatile("s_waitcnt vmcnt(" #n ")" ::: "memory")
; #define PG8_WAIT_L(n) asm volatile("s_waitcnt lgkmcnt(" #n ")" ::: "memory")
; #define PG8_BAR __builtin_amdgcn_s_barrier()
; #define PG8_SCHED __builtin_amdgcn_sched_barrier(0)
; template <class Epi, class Sched, bool ALIGN_EPI = false, bool SP2 = false>
; __device__ __forceinline__ void gemm_phase(PG8_LAS unsigned char* lds, const Gemm g, const Sched& S, const Epi& E, const int tid) {
;     ...
;             PG8_WAIT_V(8); PG8_WAIT_L(0); PG8_BAR; PG8_MMA(1, 0, At, B0); PG8_MMA(1, 1, At, B1); PG8_BAR; PG8_SCHED;
;             PG8_LDB(B0, 1, 0); PG8_LDB(B1, 1, 1); PG8_SCHED; PG8_LDA(At, 1, 0); PG8_STAGE(PG8_SA(0, 1), a2 + hstep, voffA);
;             PG8_WAIT_V(8); PG8_WAIT_L(0); PG8_BAR; PG8_MMA(0, 0, At, B0); PG8_MMA(0, 1, At, B1); PG8_BAR; PG8_SCHED;
	v_mfma_f32_16x16x32_bf16 v[24:27], v[144:147], v[202:205], v[24:27]
	v_mfma_f32_16x16x32_bf16 v[20:23], v[152:155], v[202:205], v[20:23]
	v_mfma_f32_16x16x32_bf16 v[8:11], v[144:147], v[210:213], v[8:11]
	v_mfma_f32_16x16x32_bf16 v[4:7], v[152:155], v[210:213], v[4:7]
	v_mfma_f32_16x16x32_bf16 v[56:59], v[148:151], v[190:193], v[56:59]
	v_mfma_f32_16x16x32_bf16 v[52:55], v[156:159], v[190:193], v[52:55]
	v_mfma_f32_16x16x32_bf16 v[40:43], v[148:151], v[198:201], v[40:43]
	v_mfma_f32_16x16x32_bf16 v[36:39], v[156:159], v[198:201], v[36:39]
	v_mfma_f32_16x16x32_bf16 v[24:27], v[148:151], v[206:209], v[24:27]
	v_mfma_f32_16x16x32_bf16 v[20:23], v[156:159], v[206:209], v[20:23]
	v_mfma_f32_16x16x32_bf16 v[8:11], v[148:151], v[214:217], v[8:11]
	v_mfma_f32_16x16x32_bf16 v[4:7], v[156:159], v[214:217], v[4:7]
	v_mfma_f32_16x16x32_bf16 v[60:63], v[166:169], v[186:189], v[60:63]
	v_mfma_f32_16x16x32_bf16 v[48:51], v[174:177], v[186:189], v[48:51]
	v_mfma_f32_16x16x32_bf16 v[44:47], v[166:169], v[194:197], v[44:47]
	v_mfma_f32_16x16x32_bf16 v[32:35], v[174:177], v[194:197], v[32:35]
	v_mfma_f32_16x16x32_bf16 v[28:31], v[166:169], v[202:205], v[28:31]
	v_mfma_f32_16x16x32_bf16 v[16:19], v[174:177], v[202:205], v[16:19]
	v_mfma_f32_16x16x32_bf16 v[12:15], v[166:169], v[210:213], v[12:15]
	v_mfma_f32_16x16x32_bf16 v[0:3], v[174:177], v[210:213], v[0:3]
	v_mfma_f32_16x16x32_bf16 v[60:63], v[170:173], v[190:193], v[60:63]
	v_mfma_f32_16x16x32_bf16 v[48:51], v[178:181], v[190:193], v[48:51]
	v_mfma_f32_16x16x32_bf16 v[44:47], v[170:173], v[198:201], v[44:47]
	v_mfma_f32_16x16x32_bf16 v[32:35], v[178:181], v[198:201], v[32:35]
	v_mfma_f32_16x16x32_bf16 v[28:31], v[170:173], v[206:209], v[28:31]
	v_mfma_f32_16x16x32_bf16 v[16:19], v[178:181], v[206:209], v[16:19]
	v_mfma_f32_16x16x32_bf16 v[12:15], v[170:173], v[214:217], v[12:15]
	v_mfma_f32_16x16x32_bf16 v[0:3], v[178:181], v[214:217], v[0:3]
	s_barrier
	s_setprio 0
	s_add_i32 s78, 0, 0x18000
	s_add_i32 s79, 0, 0x1c000
	v_add_u32_e32 v156, s78, v163
	v_add_u32_e32 v162, s79, v163
	ds_read_b128 v[144:147], v156
	ds_read_b128 v[148:151], v156 offset:1024
	ds_read_b128 v[152:155], v156 offset:2048
	ds_read_b128 v[156:159], v156 offset:3072
	ds_read_b128 v[166:169], v162
	ds_read_b128 v[170:173], v162 offset:1024
	ds_read_b128 v[174:177], v162 offset:2048
	ds_read_b128 v[178:181], v162 offset:3072
	s_add_u32 s60, s60, 0x80000
	s_addc_u32 s61, s61, 0
	s_mov_b32 m0, s65
	v_lshl_add_u64 v[224:225], s[60:61], 0, v[136:137]
	ds_read_b128 v[186:189], v165 offset:32768
	ds_read_b128 v[190:193], v165 offset:33792
	ds_read_b128 v[194:197], v165 offset:34816
	ds_read_b128 v[198:201], v165 offset:35840
	ds_read_b128 v[202:205], v165 offset:36864
	ds_read_b128 v[206:209], v165 offset:37888
	ds_read_b128 v[210:213], v165 offset:38912
	ds_read_b128 v[214:217], v165 offset:39936
	global_load_lds_dwordx4 v[224:225], off
	v_lshl_add_u64 v[224:225], s[60:61], 0, v[134:135]
	s_mov_b32 m0, s66
	s_nop 0
	global_load_lds_dwordx4 v[224:225], off
	s_waitcnt vmcnt(8)
	s_waitcnt lgkmcnt(0)
	s_setprio 1
	v_mfma_f32_16x16x32_bf16 v[122:125], v[144:147], v[186:189], v[122:125]
	v_mfma_f32_16x16x32_bf16 v[118:121], v[152:155], v[186:189], v[118:121]
	v_mfma_f32_16x16x32_bf16 v[110:113], v[144:147], v[194:197], v[110:113]
	v_mfma_f32_16x16x32_bf16 v[106:109], v[152:155], v[194:197], v[106:109]
	s_barrier
	v_mfma_f32_16x16x32_bf16 v[88:91], v[144:147], v[202:205], v[88:91]
	v_mfma_f32_16x16x32_bf16 v[84:87], v[152:155], v[202:205], v[84:87]
	v_mfma_f32_16x16x32_bf16 v[72:75], v[144:147], v[210:213], v[72:75]
	v_mfma_f32_16x16x32_bf16 v[68:71], v[152:155], v[210:213], v[68:71]
	v_mfma_f32_16x16x32_bf16 v[122:125], v[148:151], v[190:193], v[122:125]
	v_mfma_f32_16x16x32_bf16 v[118:121], v[156:159], v[190:193], v[118:121]
	v_mfma_f32_16x16x32_bf16 v[110:113], v[148:151], v[198:201], v[110:113]
	v_mfma_f32_16x16x32_bf16 v[106:109], v[156:159], v[198:201], v[106:109]
	v_mfma_f32_16x16x32_bf16 v[88:91], v[148:151], v[206:209], v[88:91]
	v_mfma_f32_16x16x32_bf16 v[84:87], v[156:159], v[206:209], v[84:87]
	v_mfma_f32_16x16x32_bf16 v[72:75], v[148:151], v[214:217], v[72:75]
	v_mfma_f32_16x16x32_bf16 v[68:71], v[156:159], v[214:217], v[68:71]
	v_mfma_f32_16x16x32_bf16 v[130:133], v[166:169], v[186:189], v[130:133]
	v_mfma_f32_16x16x32_bf16 v[126:129], v[174:177], v[186:189], v[126:129]
	v_mfma_f32_16x16x32_bf16 v[114:117], v[166:169], v[194:197], v[114:117]
	v_mfma_f32_16x16x32_bf16 v[102:105], v[174:177], v[194:197], v[102:105]
	v_mfma_f32_16x16x32_bf16 v[92:95], v[166:169], v[202:205], v[92:95]
	v_mfma_f32_16x16x32_bf16 v[80:83], v[174:177], v[202:205], v[80:83]
	v_mfma_f32_16x16x32_bf16 v[76:79], v[166:169], v[210:213], v[76:79]
	v_mfma_f32_16x16x32_bf16 v[64:67], v[174:177], v[210:213], v[64:67]
	v_mfma_f32_16x16x32_bf16 v[130:133], v[170:173], v[190:193], v[130:133]
	v_mfma_f32_16x16x32_bf16 v[126:129], v[178:181], v[190:193], v[126:129]
	v_mfma_f32_16x16x32_bf16 v[114:117], v[170:173], v[198:201], v[114:117]
	v_mfma_f32_16x16x32_bf16 v[102:105], v[178:181], v[198:201], v[102:105]
	v_mfma_f32_16x16x32_bf16 v[92:95], v[170:173], v[206:209], v[92:95]
	v_mfma_f32_16x16x32_bf16 v[80:83], v[178:181], v[206:209], v[80:83]
	v_mfma_f32_16x16x32_bf16 v[76:79], v[170:173], v[214:217], v[76:79]
	v_mfma_f32_16x16x32_bf16 v[64:67], v[178:181], v[214:217], v[64:67]
	s_barrier
; #define PG8_STAGE(bufoff, gbase, voff) do { _Pragma("unroll") for (int _i = 0; _i < 2; ++_i) \
;         __builtin_amdgcn_global_load_lds((const unsigned*)((const char*)(gbase) + (voff)[_i]), (PG8_LAS unsigned*)(lds + (bufoff) + ldsw + _i * 8192), 16, 0, 0); } while (0)
; #define PG8_LDA(dst, b, h) do { _Pragma("unroll") for (int m = 0; m < 4; ++m) _Pragma("unroll") for (int k = 0; k < 2; ++k) dst[m][k] = *(const PG8_LAS bf16x8*)(lds + PG8_SA(b, h) + aoff + m * 2048 + k * 1024); } while (0)
; #define PG8_MMA(ai, bj, At, Bt) do { __builtin_amdgcn_s_setprio(1); _Pragma("unroll") for (int m = 0; m < 4; ++m) _Pragma("unroll") for (int n = 0; n < 2; ++n) _Pragma("unroll") for (int k = 0; k < 2; ++k) \
;         acc[ai][bj][m][n] = __builtin_amdgcn_mfma_f32_16x16x32_bf16(Bt[n][k], At[m][k], acc[ai][bj][m][n], 0, 0, 0); __builtin_amdgcn_s_setprio(0); } while (0)
; #define PG8_WAIT_V(n) asm volatile("s_waitcnt vmcnt(" #n ")" ::: "memory")
; #define PG8_WAIT_L(n) asm volatile("s_waitcnt lgkmcnt(" #n ")" ::: "memory")
; #define PG8_BAR __builtin_amdgcn_s_barrier()
; #define PG8_SCHED __builtin_amdgcn_sched_barrier(0)
; template <class Epi, class Sched, bool ALIGN_EPI = false, bool SP2 = false>
; __device__ __forceinline__ void gemm_phase(PG8_LAS unsigned char* lds, const Gemm g, const Sched& S, const Epi& E, const int tid) {
;     ...
;             PG8_LDA(At, 1, 1); PG8_STAGE(PG8_SB(1, 0), b3, voffB); PG8_STAGE(PG8_SB(1, 1), b3 + hstep, voffB); PG8_STAGE(PG8_SA(1, 0), a3, voffA);
;             PG8_WAIT_V(8); PG8_WAIT_L(0); PG8_BAR; PG8_MMA(1, 0, At, B0); PG8_MMA(1, 1, At, B1); PG8_BAR; PG8_SCHED;
;     ...
;         if constexpr (ALIGN_EPI) { if (wr == 0) PG8_BAR; }
	s_setprio 0
	s_add_i32 s60, s78, s62
	v_lshl_add_u64 v[160:161], v[160:161], 0, s[28:29]
	s_mov_b32 m0, s60
	ds_read_b128 v[186:189], v165 offset:49152
	ds_read_b128 v[190:193], v165 offset:50176
	ds_read_b128 v[194:197], v165 offset:51200
	ds_read_b128 v[198:201], v165 offset:52224
	ds_read_b128 v[202:205], v165 offset:53248
	ds_read_b128 v[206:209], v165 offset:54272
	ds_read_b128 v[210:213], v165 offset:55296
	ds_read_b128 v[214:217], v165 offset:56320
	global_load_lds_dwordx4 v[160:161], off
	s_add_i32 m0, s60, 0x2000
	s_add_u32 s58, s58, 0x80080
	v_lshl_add_u64 v[160:161], v[218:219], 0, s[28:29]
	s_addc_u32 s59, s59, 0
	s_add_i32 s60, s79, s62
	global_load_lds_dwordx4 v[160:161], off
	v_lshl_add_u64 v[160:161], s[58:59], 0, v[96:97]
	s_mov_b32 m0, s60
	s_nop 0
	global_load_lds_dwordx4 v[160:161], off
	v_lshl_add_u64 v[160:161], s[58:59], 0, v[98:99]
	s_add_i32 m0, s60, 0x2000
	s_nop 0
	global_load_lds_dwordx4 v[160:161], off
	v_lshl_add_u64 v[160:161], v[220:221], 0, s[28:29]
	s_mov_b32 m0, s67
	s_nop 0
	global_load_lds_dwordx4 v[160:161], off
	v_lshl_add_u64 v[160:161], v[222:223], 0, s[28:29]
	s_mov_b32 m0, s68
	s_nop 0
	global_load_lds_dwordx4 v[160:161], off
	s_waitcnt vmcnt(8)
	s_waitcnt lgkmcnt(0)
	s_setprio 1
	v_mfma_f32_16x16x32_bf16 v[56:59], v[144:147], v[186:189], v[56:59]
	v_mfma_f32_16x16x32_bf16 v[52:55], v[152:155], v[186:189], v[52:55]
	v_mfma_f32_16x16x32_bf16 v[40:43], v[144:147], v[194:197], v[40:43]
	v_mfma_f32_16x16x32_bf16 v[36:39], v[152:155], v[194:197], v[36:39]
	s_barrier
	v_mfma_f32_16x16x32_bf16 v[24:27], v[144:147], v[202:205], v[24:27]
	v_mfma_f32_16x16x32_bf16 v[20:23], v[152:155], v[202:205], v[20:23]
	v_mfma_f32_16x16x32_bf16 v[8:11], v[144:147], v[210:213], v[8:11]
	v_mfma_f32_16x16x32_bf16 v[4:7], v[152:155], v[210:213], v[4:7]
	v_mfma_f32_16x16x32_bf16 v[56:59], v[148:151], v[190:193], v[56:59]
	v_mfma_f32_16x16x32_bf16 v[52:55], v[156:159], v[190:193], v[52:55]
	v_mfma_f32_16x16x32_bf16 v[40:43], v[148:151], v[198:201], v[40:43]
	v_mfma_f32_16x16x32_bf16 v[36:39], v[156:159], v[198:201], v[36:39]
	v_mfma_f32_16x16x32_bf16 v[24:27], v[148:151], v[206:209], v[24:27]
	v_mfma_f32_16x16x32_bf16 v[20:23], v[156:159], v[206:209], v[20:23]
	v_mfma_f32_16x16x32_bf16 v[8:11], v[148:151], v[214:217], v[8:11]
	v_mfma_f32_16x16x32_bf16 v[4:7], v[156:159], v[214:217], v[4:7]
	v_mfma_f32_16x16x32_bf16 v[60:63], v[166:169], v[186:189], v[60:63]
	v_mfma_f32_16x16x32_bf16 v[48:51], v[174:177], v[186:189], v[48:51]
	v_mfma_f32_16x16x32_bf16 v[44:47], v[166:169], v[194:197], v[44:47]
	v_mfma_f32_16x16x32_bf16 v[32:35], v[174:177], v[194:197], v[32:35]
	v_mfma_f32_16x16x32_bf16 v[28:31], v[166:169], v[202:205], v[28:31]
	v_mfma_f32_16x16x32_bf16 v[16:19], v[174:177], v[202:205], v[16:19]
	v_mfma_f32_16x16x32_bf16 v[12:15], v[166:169], v[210:213], v[12:15]
	v_mfma_f32_16x16x32_bf16 v[0:3], v[174:177], v[210:213], v[0:3]
	v_mfma_f32_16x16x32_bf16 v[60:63], v[170:173], v[190:193], v[60:63]
	v_mfma_f32_16x16x32_bf16 v[48:51], v[178:181], v[190:193], v[48:51]
	v_mfma_f32_16x16x32_bf16 v[44:47], v[170:173], v[198:201], v[44:47]
	v_mfma_f32_16x16x32_bf16 v[32:35], v[178:181], v[198:201], v[32:35]
	v_mfma_f32_16x16x32_bf16 v[28:31], v[170:173], v[206:209], v[28:31]
	v_mfma_f32_16x16x32_bf16 v[16:19], v[178:181], v[206:209], v[16:19]
	v_mfma_f32_16x16x32_bf16 v[12:15], v[170:173], v[214:217], v[12:15]
	v_mfma_f32_16x16x32_bf16 v[0:3], v[178:181], v[214:217], v[0:3]
	s_barrier
	s_setprio 0
	s_add_i32 s77, s77, 2
	s_add_u32 s75, s75, 0x100
	s_addc_u32 s76, s76, 0
	s_add_u32 s42, s42, 0x100
	s_addc_u32 s43, s43, 0
	s_cmp_gt_u32 s77, 29
	s_cbranch_scc0 .LBB0_488
	s_and_b64 vcc, exec, s[46:47]
	s_cbranch_vccz .LBB0_491
	s_barrier

; #define PG8_STAGE(bufoff, gbase, voff) do { _Pragma("unroll") for (int _i = 0; _i < 2; ++_i) \
;         __builtin_amdgcn_global_load_lds((const unsigned*)((const char*)(gbase) + (voff)[_i]), (PG8_LAS unsigned*)(lds + (bufoff) + ldsw + _i * 8192), 16, 0, 0); } while (0)
; #define PG8_LDA(dst, b, h) do { _Pragma("unroll") for (int m = 0; m < 4; ++m) _Pragma("unroll") for (int k = 0; k < 2; ++k) dst[m][k] = *(const PG8_LAS bf16x8*)(lds + PG8_SA(b, h) + aoff + m * 2048 + k * 1024); } while (0)
; #define PG8_LDB(dst, b, h) do { _Pragma("unroll") for (int n = 0; n < 2; ++n) _Pragma("unroll") for (int k = 0; k < 2; ++k) dst[n][k] = *(const PG8_LAS bf16x8*)(lds + PG8_SB(b, h) + boff + n * 2048 + k * 1024); } while (0)
; #define PG8_MMA(ai, bj, At, Bt) do { __builtin_amdgcn_s_setprio(1); _Pragma("unroll") for (int m = 0; m < 4; ++m) _Pragma("unroll") for (int n = 0; n < 2; ++n) _Pragma("unroll") for (int k = 0; k < 2; ++k) \
;         acc[ai][bj][m][n] = __builtin_amdgcn_mfma_f32_16x16x32_bf16(Bt[n][k], At[m][k], acc[ai][bj][m][n], 0, 0, 0); __builtin_amdgcn_s_setprio(0); } while (0)
; #define PG8_WAIT_V(n) asm volatile("s_waitcnt vmcnt(" #n ")" ::: "memory")
; #define PG8_WAIT_L(n) asm volatile("s_waitcnt lgkmcnt(" #n ")" ::: "memory")
; template <class Epi, class Sched, bool ALIGN_EPI = false, bool SP2 = false>
; __device__ __forceinline__ void gemm_phase(PG8_LAS unsigned char* lds, const Gemm g, const Sched& S, const Epi& E, const int tid) {
;     ...
;             const bool last = (t == nt - 2);
;             const char* a1 = cA + (size_t)(t + 1) * kstep;
;             const char* a2 = last ? nA : cA + (size_t)(t + 2) * kstep; const char* b2 = last ? nB : cB + (size_t)(t + 2) * kstep;
;             const char* a3 = a2 + kstep; const char* b3 = b2 + kstep;
;             if (last && has_next) S.a_ready(nxt);
;             if constexpr (SP2) {
;             PG8_LDB(B0, 0, 0); PG8_LDB(B1, 0, 1); PG8_SCHED; PG8_LDA(At, 0, 0); PG8_STAGE(PG8_SA(1, 1), a1 + hstep, voffA);
;             PG8_WAIT_V(8); PG8_WAIT_L(0); PG8_BAR; PG8_MMA(0, 0, At, B0); PG8_MMA(0, 1, At, B1); PG8_BAR; PG8_SCHED;
;             PG8_LDA(At, 0, 1); PG8_STAGE(PG8_SB(0, 0), b2, voffB); PG8_STAGE(PG8_SB(0, 1), b2 + hstep, voffB); PG8_STAGE(PG8_SA(0, 0), a2, voffA);
;             PG8_WAIT_V(8); PG8_WAIT_L(0); PG8_BAR; PG8_MMA(1, 0, At, B0); PG8_MMA(1, 1, At, B1); PG8_BAR; PG8_SCHED;
.LBB0_1199:
	s_add_u32 s56, s54, 0xfff80080
	s_addc_u32 s57, s55, -1
	s_add_i32 s77, 0, 0x10000
	s_cmp_eq_u32 s76, 28
	s_cselect_b32 s59, s49, s57
	s_cselect_b32 s58, s71, s56
	s_cselect_b32 s57, s47, s75
	s_cselect_b32 s56, s72, s73
	s_add_i32 s80, 0, 0x14000
	v_add_u32_e32 v146, s77, v233
	v_add_u32_e32 v162, s80, v233
	ds_read_b128 v[126:129], v146
	ds_read_b128 v[130:133], v146 offset:1024
	ds_read_b128 v[142:145], v146 offset:2048
	ds_read_b128 v[146:149], v146 offset:3072
	ds_read_b128 v[150:153], v162
	ds_read_b128 v[154:157], v162 offset:1024
	ds_read_b128 v[158:161], v162 offset:2048
	ds_read_b128 v[162:165], v162 offset:3072
	v_lshl_add_u64 v[210:211], s[54:55], 0, v[192:193]
	s_add_i32 m0, s62, 0xc000
	ds_read_b128 v[166:169], v236
	ds_read_b128 v[170:173], v236 offset:1024
	ds_read_b128 v[174:177], v236 offset:2048
	ds_read_b128 v[178:181], v236 offset:3072
	ds_read_b128 v[194:197], v236 offset:4096
	ds_read_b128 v[198:201], v236 offset:5120
	ds_read_b128 v[202:205], v236 offset:6144
	ds_read_b128 v[206:209], v236 offset:7168
	global_load_lds_dwordx4 v[210:211], off
	v_lshl_add_u64 v[210:211], s[54:55], 0, v[190:191]
	s_add_i32 m0, s62, 0xe000
	s_nop 0
	global_load_lds_dwordx4 v[210:211], off
	s_waitcnt vmcnt(8)
	s_waitcnt lgkmcnt(0)
	s_setprio 1
	v_mfma_f32_16x16x32_bf16 v[138:141], v[126:129], v[166:169], v[138:141]
	v_mfma_f32_16x16x32_bf16 v[134:137], v[142:145], v[166:169], v[134:137]
	v_mfma_f32_16x16x32_bf16 v[114:117], v[126:129], v[174:177], v[114:117]
	v_mfma_f32_16x16x32_bf16 v[110:113], v[142:145], v[174:177], v[110:113]
	s_barrier
	v_mfma_f32_16x16x32_bf16 v[92:95], v[126:129], v[194:197], v[92:95]
	v_mfma_f32_16x16x32_bf16 v[88:91], v[142:145], v[194:197], v[88:91]
	v_mfma_f32_16x16x32_bf16 v[76:79], v[126:129], v[202:205], v[76:79]
	v_mfma_f32_16x16x32_bf16 v[72:75], v[142:145], v[202:205], v[72:75]
	v_mfma_f32_16x16x32_bf16 v[138:141], v[130:133], v[170:173], v[138:141]
	v_mfma_f32_16x16x32_bf16 v[134:137], v[146:149], v[170:173], v[134:137]
	v_mfma_f32_16x16x32_bf16 v[114:117], v[130:133], v[178:181], v[114:117]
	v_mfma_f32_16x16x32_bf16 v[110:113], v[146:149], v[178:181], v[110:113]
	v_mfma_f32_16x16x32_bf16 v[92:95], v[130:133], v[198:201], v[92:95]
	v_mfma_f32_16x16x32_bf16 v[88:91], v[146:149], v[198:201], v[88:91]
	v_mfma_f32_16x16x32_bf16 v[76:79], v[130:133], v[206:209], v[76:79]
	v_mfma_f32_16x16x32_bf16 v[72:75], v[146:149], v[206:209], v[72:75]
	v_mfma_f32_16x16x32_bf16 v[122:125], v[150:153], v[166:169], v[122:125]
	v_mfma_f32_16x16x32_bf16 v[118:121], v[158:161], v[166:169], v[118:121]
	v_mfma_f32_16x16x32_bf16 v[106:109], v[150:153], v[174:177], v[106:109]
	v_mfma_f32_16x16x32_bf16 v[102:105], v[158:161], v[174:177], v[102:105]
	v_mfma_f32_16x16x32_bf16 v[84:87], v[150:153], v[194:197], v[84:87]
	v_mfma_f32_16x16x32_bf16 v[80:83], v[158:161], v[194:197], v[80:83]
	v_mfma_f32_16x16x32_bf16 v[68:71], v[150:153], v[202:205], v[68:71]
	v_mfma_f32_16x16x32_bf16 v[64:67], v[158:161], v[202:205], v[64:67]
	v_mfma_f32_16x16x32_bf16 v[122:125], v[154:157], v[170:173], v[122:125]
	v_mfma_f32_16x16x32_bf16 v[118:121], v[162:165], v[170:173], v[118:121]
	v_mfma_f32_16x16x32_bf16 v[106:109], v[154:157], v[178:181], v[106:109]
	v_mfma_f32_16x16x32_bf16 v[102:105], v[162:165], v[178:181], v[102:105]
	v_mfma_f32_16x16x32_bf16 v[84:87], v[154:157], v[198:201], v[84:87]
	v_mfma_f32_16x16x32_bf16 v[80:83], v[162:165], v[198:201], v[80:83]
	v_mfma_f32_16x16x32_bf16 v[68:71], v[154:157], v[206:209], v[68:71]
	v_mfma_f32_16x16x32_bf16 v[64:67], v[162:165], v[206:209], v[64:67]
	s_barrier
	s_setprio 0
	s_add_i32 s77, s77, s61
	v_lshl_add_u64 v[210:211], s[56:57], 0, v[96:97]
	s_mov_b32 m0, s77
	ds_read_b128 v[166:169], v236 offset:16384
	ds_read_b128 v[170:173], v236 offset:17408
	ds_read_b128 v[174:177], v236 offset:18432
	ds_read_b128 v[178:181], v236 offset:19456
	ds_read_b128 v[194:197], v236 offset:20480
	ds_read_b128 v[198:201], v236 offset:21504
	ds_read_b128 v[202:205], v236 offset:22528
	ds_read_b128 v[206:209], v236 offset:23552
	global_load_lds_dwordx4 v[210:211], off
	s_add_i32 m0, s77, 0x2000
	s_add_u32 s78, s56, 0x80000
	v_lshl_add_u64 v[212:213], s[56:57], 0, v[98:99]
	s_addc_u32 s79, s57, 0
	s_add_i32 s77, s80, s61
	global_load_lds_dwordx4 v[212:213], off
	v_lshl_add_u64 v[214:215], s[78:79], 0, v[96:97]
	s_mov_b32 m0, s77
	v_lshl_add_u64 v[216:217], s[58:59], 0, v[186:187]
	global_load_lds_dwordx4 v[214:215], off
	v_lshl_add_u64 v[214:215], s[78:79], 0, v[98:99]
	s_add_i32 m0, s77, 0x2000
	s_nop 0
	global_load_lds_dwordx4 v[214:215], off
	v_lshl_add_u64 v[214:215], s[58:59], 0, v[188:189]
	s_mov_b32 m0, s62
	s_nop 0
	global_load_lds_dwordx4 v[214:215], off
	s_mov_b32 m0, s63
	s_nop 0
	global_load_lds_dwordx4 v[216:217], off
	s_waitcnt vmcnt(8)
	s_waitcnt lgkmcnt(0)
	s_setprio 1
	v_mfma_f32_16x16x32_bf16 v[60:63], v[126:129], v[166:169], v[60:63]
	v_mfma_f32_16x16x32_bf16 v[56:59], v[142:145], v[166:169], v[56:59]
	v_mfma_f32_16x16x32_bf16 v[44:47], v[126:129], v[174:177], v[44:47]
	v_mfma_f32_16x16x32_bf16 v[40:43], v[142:145], v[174:177], v[40:43]
	s_barrier
; #define PG8_STAGE(bufoff, gbase, voff) do { _Pragma("unroll") for (int _i = 0; _i < 2; ++_i) \
;         __builtin_amdgcn_global_load_lds((const unsigned*)((const char*)(gbase) + (voff)[_i]), (PG8_LAS unsigned*)(lds + (bufoff) + ldsw + _i * 8192), 16, 0, 0); } while (0)
; #define PG8_LDA(dst, b, h) do { _Pragma("unroll") for (int m = 0; m < 4; ++m) _Pragma("unroll") for (int k = 0; k < 2; ++k) dst[m][k] = *(const PG8_LAS bf16x8*)(lds + PG8_SA(b, h) + aoff + m * 2048 + k * 1024); } while (0)
; #define PG8_LDB(dst, b, h) do { _Pragma("unroll") for (int n = 0; n < 2; ++n) _Pragma("unroll") for (int k = 0; k < 2; ++k) dst[n][k] = *(const PG8_LAS bf16x8*)(lds + PG8_SB(b, h) + boff + n * 2048 + k * 1024); } while (0)
; #define PG8_MMA(ai, bj, At, Bt) do { __builtin_amdgcn_s_setprio(1); _Pragma("unroll") for (int m = 0; m < 4; ++m) _Pragma("unroll") for (int n = 0; n < 2; ++n) _Pragma("unroll") for (int k = 0; k < 2; ++k) \
;         acc[ai][bj][m][n] = __builtin_amdgcn_mfma_f32_16x16x32_bf16(Bt[n][k], At[m][k], acc[ai][bj][m][n], 0, 0, 0); __builtin_amdgcn_s_setprio(0); } while (0)
; #define PG8_WAIT_V(n) asm volatile("s_waitcnt vmcnt(" #n ")" ::: "memory")
; #define PG8_WAIT_L(n) asm volatile("s_waitcnt lgkmcnt(" #n ")" ::: "memory")
; #define PG8_BAR __builtin_amdgcn_s_barrier()
; #define PG8_SCHED __builtin_amdgcn_sched_barrier(0)
; template <class Epi, class Sched, bool ALIGN_EPI = false, bool SP2 = false>
; __device__ __forceinline__ void gemm_phase(PG8_LAS unsigned char* lds, const Gemm g, const Sched& S, const Epi& E, const int tid) {
;     ...
;             PG8_WAIT_V(8); PG8_WAIT_L(0); PG8_BAR; PG8_MMA(1, 0, At, B0); PG8_MMA(1, 1, At, B1); PG8_BAR; PG8_SCHED;
;             PG8_LDB(B0, 1, 0); PG8_LDB(B1, 1, 1); PG8_SCHED; PG8_LDA(At, 1, 0); PG8_STAGE(PG8_SA(0, 1), a2 + hstep, voffA);
;             PG8_WAIT_V(8); PG8_WAIT_L(0); PG8_BAR; PG8_MMA(0, 0, At, B0); PG8_MMA(0, 1, At, B1); PG8_BAR; PG8_SCHED;
	v_mfma_f32_16x16x32_bf16 v[28:31], v[126:129], v[194:197], v[28:31]
	v_mfma_f32_16x16x32_bf16 v[24:27], v[142:145], v[194:197], v[24:27]
	v_mfma_f32_16x16x32_bf16 v[12:15], v[126:129], v[202:205], v[12:15]
	v_mfma_f32_16x16x32_bf16 v[8:11], v[142:145], v[202:205], v[8:11]
	v_mfma_f32_16x16x32_bf16 v[60:63], v[130:133], v[170:173], v[60:63]
	v_mfma_f32_16x16x32_bf16 v[56:59], v[146:149], v[170:173], v[56:59]
	v_mfma_f32_16x16x32_bf16 v[44:47], v[130:133], v[178:181], v[44:47]
	v_mfma_f32_16x16x32_bf16 v[40:43], v[146:149], v[178:181], v[40:43]
	v_mfma_f32_16x16x32_bf16 v[28:31], v[130:133], v[198:201], v[28:31]
	v_mfma_f32_16x16x32_bf16 v[24:27], v[146:149], v[198:201], v[24:27]
	v_mfma_f32_16x16x32_bf16 v[12:15], v[130:133], v[206:209], v[12:15]
	v_mfma_f32_16x16x32_bf16 v[8:11], v[146:149], v[206:209], v[8:11]
	v_mfma_f32_16x16x32_bf16 v[52:55], v[150:153], v[166:169], v[52:55]
	v_mfma_f32_16x16x32_bf16 v[48:51], v[158:161], v[166:169], v[48:51]
	v_mfma_f32_16x16x32_bf16 v[36:39], v[150:153], v[174:177], v[36:39]
	v_mfma_f32_16x16x32_bf16 v[32:35], v[158:161], v[174:177], v[32:35]
	v_mfma_f32_16x16x32_bf16 v[20:23], v[150:153], v[194:197], v[20:23]
	v_mfma_f32_16x16x32_bf16 v[16:19], v[158:161], v[194:197], v[16:19]
	v_mfma_f32_16x16x32_bf16 v[4:7], v[150:153], v[202:205], v[4:7]
	v_mfma_f32_16x16x32_bf16 v[0:3], v[158:161], v[202:205], v[0:3]
	v_mfma_f32_16x16x32_bf16 v[52:55], v[154:157], v[170:173], v[52:55]
	v_mfma_f32_16x16x32_bf16 v[48:51], v[162:165], v[170:173], v[48:51]
	v_mfma_f32_16x16x32_bf16 v[36:39], v[154:157], v[178:181], v[36:39]
	v_mfma_f32_16x16x32_bf16 v[32:35], v[162:165], v[178:181], v[32:35]
	v_mfma_f32_16x16x32_bf16 v[20:23], v[154:157], v[198:201], v[20:23]
	v_mfma_f32_16x16x32_bf16 v[16:19], v[162:165], v[198:201], v[16:19]
	v_mfma_f32_16x16x32_bf16 v[4:7], v[154:157], v[206:209], v[4:7]
	v_mfma_f32_16x16x32_bf16 v[0:3], v[162:165], v[206:209], v[0:3]
	s_barrier
	s_setprio 0
	s_add_i32 s77, 0, 0x18000
	s_add_i32 s78, 0, 0x1c000
	v_add_u32_e32 v146, s77, v233
	v_add_u32_e32 v162, s78, v233
	ds_read_b128 v[126:129], v146
	ds_read_b128 v[130:133], v146 offset:1024
	ds_read_b128 v[142:145], v146 offset:2048
	ds_read_b128 v[146:149], v146 offset:3072
	ds_read_b128 v[150:153], v162
	ds_read_b128 v[154:157], v162 offset:1024
	ds_read_b128 v[158:161], v162 offset:2048
	ds_read_b128 v[162:165], v162 offset:3072
	s_add_u32 s58, s58, 0x80000
	s_addc_u32 s59, s59, 0
	s_mov_b32 m0, s64
	v_lshl_add_u64 v[218:219], s[58:59], 0, v[188:189]
	ds_read_b128 v[166:169], v236 offset:32768
	ds_read_b128 v[170:173], v236 offset:33792
	ds_read_b128 v[174:177], v236 offset:34816
	ds_read_b128 v[178:181], v236 offset:35840
	ds_read_b128 v[194:197], v236 offset:36864
	ds_read_b128 v[198:201], v236 offset:37888
	ds_read_b128 v[202:205], v236 offset:38912
	ds_read_b128 v[206:209], v236 offset:39936
	global_load_lds_dwordx4 v[218:219], off
	v_lshl_add_u64 v[218:219], s[58:59], 0, v[186:187]
	s_mov_b32 m0, s65
	s_nop 0
	global_load_lds_dwordx4 v[218:219], off
	s_waitcnt vmcnt(8)
	s_waitcnt lgkmcnt(0)
	s_setprio 1
	v_mfma_f32_16x16x32_bf16 v[138:141], v[126:129], v[166:169], v[138:141]
	v_mfma_f32_16x16x32_bf16 v[134:137], v[142:145], v[166:169], v[134:137]
	v_mfma_f32_16x16x32_bf16 v[114:117], v[126:129], v[174:177], v[114:117]
	v_mfma_f32_16x16x32_bf16 v[110:113], v[142:145], v[174:177], v[110:113]
	s_barrier
	v_mfma_f32_16x16x32_bf16 v[92:95], v[126:129], v[194:197], v[92:95]
	v_mfma_f32_16x16x32_bf16 v[88:91], v[142:145], v[194:197], v[88:91]
	v_mfma_f32_16x16x32_bf16 v[76:79], v[126:129], v[202:205], v[76:79]
	v_mfma_f32_16x16x32_bf16 v[72:75], v[142:145], v[202:205], v[72:75]
	v_mfma_f32_16x16x32_bf16 v[138:141], v[130:133], v[170:173], v[138:141]
	v_mfma_f32_16x16x32_bf16 v[134:137], v[146:149], v[170:173], v[134:137]
	v_mfma_f32_16x16x32_bf16 v[114:117], v[130:133], v[178:181], v[114:117]
	v_mfma_f32_16x16x32_bf16 v[110:113], v[146:149], v[178:181], v[110:113]
	v_mfma_f32_16x16x32_bf16 v[92:95], v[130:133], v[198:201], v[92:95]
	v_mfma_f32_16x16x32_bf16 v[88:91], v[146:149], v[198:201], v[88:91]
	v_mfma_f32_16x16x32_bf16 v[76:79], v[130:133], v[206:209], v[76:79]
	v_mfma_f32_16x16x32_bf16 v[72:75], v[146:149], v[206:209], v[72:75]
	v_mfma_f32_16x16x32_bf16 v[122:125], v[150:153], v[166:169], v[122:125]
	v_mfma_f32_16x16x32_bf16 v[118:121], v[158:161], v[166:169], v[118:121]
	v_mfma_f32_16x16x32_bf16 v[106:109], v[150:153], v[174:177], v[106:109]
	v_mfma_f32_16x16x32_bf16 v[102:105], v[158:161], v[174:177], v[102:105]
	v_mfma_f32_16x16x32_bf16 v[84:87], v[150:153], v[194:197], v[84:87]
	v_mfma_f32_16x16x32_bf16 v[80:83], v[158:161], v[194:197], v[80:83]
	v_mfma_f32_16x16x32_bf16 v[68:71], v[150:153], v[202:205], v[68:71]
	v_mfma_f32_16x16x32_bf16 v[64:67], v[158:161], v[202:205], v[64:67]
	v_mfma_f32_16x16x32_bf16 v[122:125], v[154:157], v[170:173], v[122:125]
	v_mfma_f32_16x16x32_bf16 v[118:121], v[162:165], v[170:173], v[118:121]
	v_mfma_f32_16x16x32_bf16 v[106:109], v[154:157], v[178:181], v[106:109]
	v_mfma_f32_16x16x32_bf16 v[102:105], v[162:165], v[178:181], v[102:105]
	v_mfma_f32_16x16x32_bf16 v[84:87], v[154:157], v[198:201], v[84:87]
	v_mfma_f32_16x16x32_bf16 v[80:83], v[162:165], v[198:201], v[80:83]
	v_mfma_f32_16x16x32_bf16 v[68:71], v[154:157], v[206:209], v[68:71]
	v_mfma_f32_16x16x32_bf16 v[64:67], v[162:165], v[206:209], v[64:67]
	s_barrier
; #define PG8_GAS __attribute__((address_space(1)))
; #define PG8_STAGE(bufoff, gbase, voff) do { _Pragma("unroll") for (int _i = 0; _i < 2; ++_i) \
;         __builtin_amdgcn_global_load_lds((const unsigned*)((const char*)(gbase) + (voff)[_i]), (PG8_LAS unsigned*)(lds + (bufoff) + ldsw + _i * 8192), 16, 0, 0); } while (0)
; #define PG8_LDA(dst, b, h) do { _Pragma("unroll") for (int m = 0; m < 4; ++m) _Pragma("unroll") for (int k = 0; k < 2; ++k) dst[m][k] = *(const PG8_LAS bf16x8*)(lds + PG8_SA(b, h) + aoff + m * 2048 + k * 1024); } while (0)
; #define PG8_MMA(ai, bj, At, Bt) do { __builtin_amdgcn_s_setprio(1); _Pragma("unroll") for (int m = 0; m < 4; ++m) _Pragma("unroll") for (int n = 0; n < 2; ++n) _Pragma("unroll") for (int k = 0; k < 2; ++k) \
;         acc[ai][bj][m][n] = __builtin_amdgcn_mfma_f32_16x16x32_bf16(Bt[n][k], At[m][k], acc[ai][bj][m][n], 0, 0, 0); __builtin_amdgcn_s_setprio(0); } while (0)
; #define PG8_WAIT_V(n) asm volatile("s_waitcnt vmcnt(" #n ")" ::: "memory")
; #define PG8_WAIT_L(n) asm volatile("s_waitcnt lgkmcnt(" #n ")" ::: "memory")
; #define PG8_BAR __builtin_amdgcn_s_barrier()
;     __device__ __forceinline__ void operator()(const f32x4 (&acc)[2][2][4][2], const Unit& u, int wr, int wc, int fr, int fq) const {
;         const int row0 = u.pm * BM + wr * 64 + fr, col0 = u.pn * BM + wc * 32 + 8 * fq, lcol = u.pn * BM + (wc * 4 + fq) * 16;
; #pragma unroll
;         for (int ai = 0; ai < 2; ++ai) {
;             u32x4 L4[4], H4[4][2];
; #pragma unroll
;             for (int m = 0; m < 4; ++m) {
;                 const int row = row0 + ai * HALF + m * 16; const size_t off = (size_t)row * 2048 + col0, loff = (size_t)row * 2048 + lcol;
;                 L4[m] = *(const PG8_GAS u32x4*)(lin + loff); H4[m][0] = *(const PG8_GAS u32x4*)(hin + off); H4[m][1] = *(const PG8_GAS u32x4*)(hin + off + HALF);
;             }
; template <class Epi, class Sched, bool ALIGN_EPI = false, bool SP2 = false>
; __device__ __forceinline__ void gemm_phase(PG8_LAS unsigned char* lds, const Gemm g, const Sched& S, const Epi& E, const int tid) {
;     ...
;             PG8_LDA(At, 1, 1); PG8_STAGE(PG8_SB(1, 0), b3, voffB); PG8_STAGE(PG8_SB(1, 1), b3 + hstep, voffB); PG8_STAGE(PG8_SA(1, 0), a3, voffA);
;             PG8_WAIT_V(8); PG8_WAIT_L(0); PG8_BAR; PG8_MMA(1, 0, At, B0); PG8_MMA(1, 1, At, B1); PG8_BAR; PG8_SCHED;
	s_setprio 0
	s_add_i32 s58, s77, s61
	v_lshl_add_u64 v[210:211], v[210:211], 0, s[28:29]
	s_mov_b32 m0, s58
	ds_read_b128 v[166:169], v236 offset:49152
	ds_read_b128 v[170:173], v236 offset:50176
	ds_read_b128 v[174:177], v236 offset:51200
	ds_read_b128 v[178:181], v236 offset:52224
	ds_read_b128 v[194:197], v236 offset:53248
	ds_read_b128 v[198:201], v236 offset:54272
	ds_read_b128 v[202:205], v236 offset:55296
	ds_read_b128 v[206:209], v236 offset:56320
	global_load_lds_dwordx4 v[210:211], off
	s_add_i32 m0, s58, 0x2000
	s_add_u32 s56, s56, 0x80080
	v_lshl_add_u64 v[210:211], v[212:213], 0, s[28:29]
	s_addc_u32 s57, s57, 0
	s_add_i32 s58, s78, s61
	global_load_lds_dwordx4 v[210:211], off
	v_lshl_add_u64 v[210:211], s[56:57], 0, v[96:97]
	s_mov_b32 m0, s58
	s_nop 0
	global_load_lds_dwordx4 v[210:211], off
	v_lshl_add_u64 v[210:211], s[56:57], 0, v[98:99]
	s_add_i32 m0, s58, 0x2000
	s_nop 0
	global_load_lds_dwordx4 v[210:211], off
	v_lshl_add_u64 v[210:211], v[214:215], 0, s[28:29]
	s_mov_b32 m0, s66
	s_nop 0
	global_load_lds_dwordx4 v[210:211], off
	v_lshl_add_u64 v[210:211], v[216:217], 0, s[28:29]
	s_mov_b32 m0, s67
	s_nop 0
	global_load_lds_dwordx4 v[210:211], off
	s_waitcnt vmcnt(8)
	s_waitcnt lgkmcnt(0)
	s_setprio 1
	v_mfma_f32_16x16x32_bf16 v[60:63], v[126:129], v[166:169], v[60:63]
	v_mfma_f32_16x16x32_bf16 v[56:59], v[142:145], v[166:169], v[56:59]
	v_mfma_f32_16x16x32_bf16 v[44:47], v[126:129], v[174:177], v[44:47]
	v_mfma_f32_16x16x32_bf16 v[40:43], v[142:145], v[174:177], v[40:43]
	s_barrier
	v_mfma_f32_16x16x32_bf16 v[28:31], v[126:129], v[194:197], v[28:31]
	v_mfma_f32_16x16x32_bf16 v[24:27], v[142:145], v[194:197], v[24:27]
	v_mfma_f32_16x16x32_bf16 v[12:15], v[126:129], v[202:205], v[12:15]
	v_mfma_f32_16x16x32_bf16 v[8:11], v[142:145], v[202:205], v[8:11]
	v_mfma_f32_16x16x32_bf16 v[60:63], v[130:133], v[170:173], v[60:63]
	v_mfma_f32_16x16x32_bf16 v[56:59], v[146:149], v[170:173], v[56:59]
	v_mfma_f32_16x16x32_bf16 v[44:47], v[130:133], v[178:181], v[44:47]
	v_mfma_f32_16x16x32_bf16 v[40:43], v[146:149], v[178:181], v[40:43]
	v_mfma_f32_16x16x32_bf16 v[28:31], v[130:133], v[198:201], v[28:31]
	v_mfma_f32_16x16x32_bf16 v[24:27], v[146:149], v[198:201], v[24:27]
	v_mfma_f32_16x16x32_bf16 v[12:15], v[130:133], v[206:209], v[12:15]
	v_mfma_f32_16x16x32_bf16 v[8:11], v[146:149], v[206:209], v[8:11]
	v_mfma_f32_16x16x32_bf16 v[52:55], v[150:153], v[166:169], v[52:55]
	v_mfma_f32_16x16x32_bf16 v[48:51], v[158:161], v[166:169], v[48:51]
	v_mfma_f32_16x16x32_bf16 v[36:39], v[150:153], v[174:177], v[36:39]
	v_mfma_f32_16x16x32_bf16 v[32:35], v[158:161], v[174:177], v[32:35]
	v_mfma_f32_16x16x32_bf16 v[20:23], v[150:153], v[194:197], v[20:23]
	v_mfma_f32_16x16x32_bf16 v[16:19], v[158:161], v[194:197], v[16:19]
	v_mfma_f32_16x16x32_bf16 v[4:7], v[150:153], v[202:205], v[4:7]
	v_mfma_f32_16x16x32_bf16 v[0:3], v[158:161], v[202:205], v[0:3]
	v_mfma_f32_16x16x32_bf16 v[52:55], v[154:157], v[170:173], v[52:55]
	v_mfma_f32_16x16x32_bf16 v[48:51], v[162:165], v[170:173], v[48:51]
	v_mfma_f32_16x16x32_bf16 v[36:39], v[154:157], v[178:181], v[36:39]
	v_mfma_f32_16x16x32_bf16 v[32:35], v[162:165], v[178:181], v[32:35]
	v_mfma_f32_16x16x32_bf16 v[20:23], v[154:157], v[198:201], v[20:23]
	v_mfma_f32_16x16x32_bf16 v[16:19], v[162:165], v[198:201], v[16:19]
	v_mfma_f32_16x16x32_bf16 v[4:7], v[154:157], v[206:209], v[4:7]
	v_mfma_f32_16x16x32_bf16 v[0:3], v[162:165], v[206:209], v[0:3]
	s_barrier
	s_setprio 0
	s_add_i32 s76, s76, 2
	s_add_u32 s73, s73, 0x100
	s_addc_u32 s75, s75, 0
	s_add_u32 s54, s54, 0x100
	s_addc_u32 s55, s55, 0
	s_cmp_gt_u32 s76, 29
	s_cbranch_scc0 .LBB0_1199
	v_and_b32_e32 v127, 64, v228
	v_xor_b32_e32 v126, 16, v228
	v_add_u32_e32 v127, 64, v127
	v_cmp_lt_i32_e32 vcc, v126, v127
	s_lshl_b32 s47, s69, 8
	v_lshl_add_u32 v198, s70, 8, v101
	v_cndmask_b32_e32 v126, v228, v126, vcc
	v_or_b32_e32 v194, s47, v235
	v_lshlrev_b32_e32 v238, 2, v126
	v_xor_b32_e32 v126, 32, v228
	v_or_b32_e32 v196, s47, v234
	v_ashrrev_i32_e32 v195, 31, v194
	v_cmp_lt_i32_e32 vcc, v126, v127
	v_ashrrev_i32_e32 v199, 31, v198
	v_ashrrev_i32_e32 v197, 31, v196
	v_cndmask_b32_e32 v126, v228, v126, vcc
	v_lshl_add_u64 v[202:203], s[34:35], 0, v[194:195]
	v_lshlrev_b64 v[216:217], 11, v[198:199]
	v_lshlrev_b32_e32 v237, 2, v126
	v_lshlrev_b64 v[218:219], 1, v[196:197]
	v_lshl_add_u64 v[126:127], v[202:203], 0, v[216:217]
	v_lshl_add_u64 v[200:201], s[30:31], 0, v[218:219]
	global_load_dwordx4 v[170:173], v[126:127], off
	v_lshlrev_b64 v[220:221], 12, v[198:199]
	v_lshl_add_u64 v[126:127], v[200:201], 0, v[220:221]
	global_load_dwordx4 v[178:181], v[126:127], off
	global_load_dwordx4 v[174:177], v[126:127], off offset:256
	v_or_b32_e32 v212, 16, v198
	v_ashrrev_i32_e32 v213, 31, v212
	v_lshlrev_b64 v[214:215], 11, v[212:213]
	v_lshl_add_u64 v[126:127], v[202:203], 0, v[214:215]
	v_or_b32_e32 v208, 32, v198
	global_load_dwordx4 v[158:161], v[126:127], off
	v_lshlrev_b64 v[126:127], 12, v[212:213]
	v_ashrrev_i32_e32 v209, 31, v208
	v_lshl_add_u64 v[126:127], v[200:201], 0, v[126:127]
	v_lshlrev_b64 v[210:211], 11, v[208:209]
	global_load_dwordx4 v[166:169], v[126:127], off
	global_load_dwordx4 v[162:165], v[126:127], off offset:256
	v_lshl_add_u64 v[126:127], v[202:203], 0, v[210:211]
	v_or_b32_e32 v204, 48, v198
	global_load_dwordx4 v[146:149], v[126:127], off
	v_lshlrev_b64 v[126:127], 12, v[208:209]
	v_ashrrev_i32_e32 v205, 31, v204
	v_lshl_add_u64 v[126:127], v[200:201], 0, v[126:127]
	v_lshlrev_b64 v[206:207], 11, v[204:205]
	v_lshlrev_b64 v[130:131], 12, v[204:205]
	global_load_dwordx4 v[154:157], v[126:127], off
	global_load_dwordx4 v[150:153], v[126:127], off offset:256
	v_lshl_add_u64 v[126:127], v[202:203], 0, v[206:207]
	v_lshl_add_u64 v[130:131], v[200:201], 0, v[130:131]
	global_load_dwordx4 v[126:129], v[126:127], off
	s_nop 0
	global_load_dwordx4 v[142:145], v[130:131], off
	s_nop 0
	global_load_dwordx4 v[130:133], v[130:131], off offset:256
	v_mov_b32_e32 v225, v134
	v_mov_b32_e32 v243, v136
	v_mov_b32_e32 v242, v140
	s_waitcnt vmcnt(0)
; #define PG8_GAS __attribute__((address_space(1)))
; __device__ __forceinline__ float e_x24(unsigned h16, unsigned l8) { return __uint_as_float(((h16 - (l8 >> 7)) << 16) | (l8 << 8)); }
;     __device__ __forceinline__ void operator()(const f32x4 (&acc)[2][2][4][2], const Unit& u, int wr, int wc, int fr, int fq) const {
;     ...
;             for (int m = 0; m < 4; ++m) {
;                 const int row = row0 + ai * HALF + m * 16; const size_t off = (size_t)row * 2048 + col0, loff = (size_t)row * 2048 + lcol; float ss = 0.f;
;                 const u32x4 l4 = L4[m];
;                 u32x4 lo4;
; #pragma unroll
;                 for (int bj = 0; bj < 2; ++bj) {
;                     const u32x4 h4 = H4[m][bj];
;                     u32x4 ho;
; #pragma unroll
;                     for (int j = 0; j < 4; ++j) {
;                         const unsigned lw = l4[2 * bj + (j >> 1)], lb0 = (lw >> (16 * (j & 1))) & 0xffu, lb1 = (lw >> (16 * (j & 1) + 8)) & 0xffu;
;                         const float x0 = e_x24(h4[j] & 0xffffu, lb0) + acc[ai][bj][m][j >> 1][2 * (j & 1)] * scale, x1 = e_x24(h4[j] >> 16, lb1) + acc[ai][bj][m][j >> 1][2 * (j & 1) + 1] * scale;
;                         const unsigned b0 = __float_as_uint(x0), b1 = __float_as_uint(x1);
;                         ho[j] = ((b0 + 0x8000u) >> 16) | ((b1 + 0x8000u) & 0xffff0000u);
;                         const unsigned nb = ((b0 >> 8) & 0xffu) | (b1 & 0xff00u);
;                         if ((j & 1) == 0) lo4[2 * bj + (j >> 1)] = nb; else lo4[2 * bj + (j >> 1)] |= nb << 16;
;                         ss += x0 * x0 + x1 * x1;
;                     }
;                     *(PG8_GAS u32x4*)(hout + off + bj * HALF) = ho;
;                 }
	v_lshrrev_b32_sdwa v182, v229, v171 dst_sel:DWORD dst_unused:UNUSED_PAD src0_sel:DWORD src1_sel:BYTE_0
	v_lshrrev_b32_sdwa v183, v229, v170 dst_sel:DWORD dst_unused:UNUSED_PAD src0_sel:DWORD src1_sel:BYTE_0
	v_sub_u32_sdwa v183, v178, v183 dst_sel:WORD_1 dst_unused:UNUSED_PAD src0_sel:DWORD src1_sel:DWORD
	v_sub_u32_sdwa v182, v180, v182 dst_sel:WORD_1 dst_unused:UNUSED_PAD src0_sel:DWORD src1_sel:DWORD
	v_lshlrev_b32_sdwa v222, v230, v171 dst_sel:DWORD dst_unused:UNUSED_PAD src0_sel:DWORD src1_sel:BYTE_0
	v_lshlrev_b32_sdwa v224, v230, v170 dst_sel:DWORD dst_unused:UNUSED_PAD src0_sel:DWORD src1_sel:BYTE_0
	v_or_b32_e32 v223, v182, v222
	v_or_b32_e32 v222, v183, v224
	v_mov_b32_e32 v224, v138
	v_pk_add_f32 v[222:223], v[224:225], v[222:223]
	v_lshlrev_b32_e32 v182, 1, v170
	v_add_u32_e32 v134, 0x8000, v222
	v_lshrrev_b32_e32 v138, 16, v134
	v_lshlrev_b32_e32 v134, 1, v171
	v_and_b32_e32 v134, 0x10000, v134
	v_and_b32_e32 v182, 0x10000, v182
	v_sub_u32_e32 v134, v180, v134
	v_sub_u32_e32 v178, v178, v182
	v_and_b32_e32 v134, 0xffff0000, v134
	v_and_b32_e32 v178, 0xffff0000, v178
	v_and_b32_e32 v180, 0xff00, v171
	v_and_b32_e32 v182, 0xff00, v170
	v_or_b32_e32 v225, v134, v180
	v_or_b32_e32 v224, v178, v182
	v_mov_b32_e32 v134, v139
	v_pk_add_f32 v[224:225], v[134:135], v[224:225]
	v_and_b32_sdwa v135, v171, s93 dst_sel:DWORD dst_unused:UNUSED_PAD src0_sel:WORD_1 src1_sel:DWORD
	v_and_b32_sdwa v178, v170, s93 dst_sel:DWORD dst_unused:UNUSED_PAD src0_sel:WORD_1 src1_sel:DWORD
	v_lshlrev_b32_sdwa v182, v231, v170 dst_sel:DWORD dst_unused:UNUSED_PAD src0_sel:DWORD src1_sel:BYTE_3
	v_lshlrev_b32_sdwa v136, v231, v171 dst_sel:DWORD dst_unused:UNUSED_PAD src0_sel:DWORD src1_sel:BYTE_3
	v_lshrrev_b32_e32 v180, 7, v178
	v_lshrrev_b32_e32 v183, 7, v135
	v_and_b32_e32 v136, 0x10000, v136
	v_and_b32_e32 v140, 0x10000, v182
	v_sub_u32_sdwa v180, v179, v180 dst_sel:WORD_1 dst_unused:UNUSED_PAD src0_sel:DWORD src1_sel:DWORD
	v_sub_u32_sdwa v183, v181, v183 dst_sel:WORD_1 dst_unused:UNUSED_PAD src0_sel:DWORD src1_sel:DWORD
	v_lshlrev_b32_e32 v135, 8, v135
	v_lshlrev_b32_e32 v178, 8, v178
	v_sub_u32_e32 v136, v181, v136
	v_sub_u32_e32 v140, v179, v140
	v_or_b32_e32 v241, v183, v135
	v_or_b32_e32 v240, v180, v178
	v_and_b32_e32 v136, 0xffff0000, v136
	v_and_b32_e32 v140, 0xffff0000, v140
	v_lshlrev_b32_sdwa v171, v230, v171 dst_sel:DWORD dst_unused:UNUSED_PAD src0_sel:DWORD src1_sel:BYTE_3
	v_lshlrev_b32_sdwa v170, v230, v170 dst_sel:DWORD dst_unused:UNUSED_PAD src0_sel:DWORD src1_sel:BYTE_3
	v_pk_add_f32 v[240:241], v[242:243], v[240:241]
	v_or_b32_e32 v171, v136, v171
	v_or_b32_e32 v170, v140, v170
	v_mov_b32_e32 v136, v141
	v_add_u32_e32 v135, 0x8000, v240
	v_pk_add_f32 v[140:141], v[136:137], v[170:171]
	v_lshrrev_b32_e32 v135, 16, v135
	v_add_u32_e32 v136, 0x8000, v140
	v_and_or_b32 v135, v136, s90, v135
	v_pk_mul_f32 v[136:137], v[140:141], v[140:141]
	v_add_u32_e32 v178, 0x8000, v141
	v_pk_fma_f32 v[170:171], v[240:241], v[240:241], v[136:137]
	v_add_u32_e32 v136, 0x8000, v223
	v_lshrrev_b32_e32 v136, 16, v136
	v_add_u32_e32 v137, 0x8000, v225
	v_and_or_b32 v136, v137, s90, v136
	v_add_u32_e32 v137, 0x8000, v241
	v_lshrrev_b32_e32 v137, 16, v137
	v_add_u32_e32 v134, 0x8000, v224
	v_and_or_b32 v137, v178, s90, v137
	v_lshl_add_u64 v[178:179], s[30:31], 0, v[220:221]
	v_and_or_b32 v134, v134, s90, v138
	v_lshl_add_u64 v[178:179], v[178:179], 0, v[218:219]
	global_store_dwordx4 v[178:179], v[134:137], off
	v_lshlrev_b32_sdwa v182, v231, v172 dst_sel:DWORD dst_unused:UNUSED_PAD src0_sel:DWORD src1_sel:BYTE_3
	v_mov_b32_e32 v219, v120
	v_lshrrev_b32_sdwa v134, v229, v173 dst_sel:DWORD dst_unused:UNUSED_PAD src0_sel:DWORD src1_sel:BYTE_0
	v_lshrrev_b32_sdwa v135, v229, v172 dst_sel:DWORD dst_unused:UNUSED_PAD src0_sel:DWORD src1_sel:BYTE_0
	v_sub_u32_sdwa v136, v174, v135 dst_sel:WORD_1 dst_unused:UNUSED_PAD src0_sel:DWORD src1_sel:DWORD
	v_sub_u32_sdwa v134, v176, v134 dst_sel:WORD_1 dst_unused:UNUSED_PAD src0_sel:DWORD src1_sel:DWORD
	v_lshlrev_b32_sdwa v135, v230, v173 dst_sel:DWORD dst_unused:UNUSED_PAD src0_sel:DWORD src1_sel:BYTE_0
	v_lshlrev_b32_sdwa v137, v230, v172 dst_sel:DWORD dst_unused:UNUSED_PAD src0_sel:DWORD src1_sel:BYTE_0
	v_or_b32_e32 v135, v134, v135
	v_or_b32_e32 v134, v136, v137
	v_mov_b32_e32 v136, v122
	v_mov_b32_e32 v137, v118
	v_pk_add_f32 v[134:135], v[136:137], v[134:135]
	v_lshlrev_b32_e32 v122, 1, v172
; #define PG8_GAS __attribute__((address_space(1)))
; __device__ __forceinline__ float e_x24(unsigned h16, unsigned l8) { return __uint_as_float(((h16 - (l8 >> 7)) << 16) | (l8 << 8)); }
;     __device__ __forceinline__ void operator()(const f32x4 (&acc)[2][2][4][2], const Unit& u, int wr, int wc, int fr, int fq) const {
;     ...
;                         const float x0 = e_x24(h4[j] & 0xffffu, lb0) + acc[ai][bj][m][j >> 1][2 * (j & 1)] * scale, x1 = e_x24(h4[j] >> 16, lb1) + acc[ai][bj][m][j >> 1][2 * (j & 1) + 1] * scale;
;                         const unsigned b0 = __float_as_uint(x0), b1 = __float_as_uint(x1);
;                         ho[j] = ((b0 + 0x8000u) >> 16) | ((b1 + 0x8000u) & 0xffff0000u);
;                         const unsigned nb = ((b0 >> 8) & 0xffu) | (b1 & 0xff00u);
;                         if ((j & 1) == 0) lo4[2 * bj + (j >> 1)] = nb; else lo4[2 * bj + (j >> 1)] |= nb << 16;
;                         ss += x0 * x0 + x1 * x1;
;                     }
;                     *(PG8_GAS u32x4*)(hout + off + bj * HALF) = ho;
;                 }
;                 *(PG8_GAS u32x4*)(lout + loff) = lo4;
;                 ss += __shfl_xor(ss, 16); ss += __shfl_xor(ss, 32);
;                 if (fq == 0) __hip_atomic_fetch_add((PG8_GAS unsigned long long*)(rowsq_out + row), (unsigned long long)(ss * 16777216.0f + 0.5f), __ATOMIC_RELAXED, __HIP_MEMORY_SCOPE_AGENT);
	v_add_u32_e32 v118, 0x8000, v134
	v_lshrrev_b32_e32 v180, 16, v118
	v_lshlrev_b32_e32 v118, 1, v173
	v_and_b32_e32 v118, 0x10000, v118
	v_and_b32_e32 v122, 0x10000, v122
	v_sub_u32_e32 v118, v176, v118
	v_sub_u32_e32 v122, v174, v122
	v_and_b32_e32 v118, 0xffff0000, v118
	v_and_b32_e32 v122, 0xffff0000, v122
	v_and_b32_e32 v136, 0xff00, v173
	v_and_b32_e32 v174, 0xff00, v172
	v_or_b32_e32 v137, v118, v136
	v_or_b32_e32 v136, v122, v174
	v_mov_b32_e32 v118, v123
	v_pk_add_f32 v[122:123], v[118:119], v[136:137]
	v_and_b32_sdwa v119, v173, s93 dst_sel:DWORD dst_unused:UNUSED_PAD src0_sel:WORD_1 src1_sel:DWORD
	v_add_u32_e32 v118, 0x8000, v122
	v_and_b32_sdwa v174, v172, s93 dst_sel:DWORD dst_unused:UNUSED_PAD src0_sel:WORD_1 src1_sel:DWORD
	v_lshlrev_b32_sdwa v120, v231, v173 dst_sel:DWORD dst_unused:UNUSED_PAD src0_sel:DWORD src1_sel:BYTE_3
	v_and_or_b32 v118, v118, s90, v180
	v_lshrrev_b32_e32 v176, 7, v174
	v_lshrrev_b32_e32 v180, 7, v119
	v_mov_b32_e32 v218, v124
	v_and_b32_e32 v120, 0x10000, v120
	v_and_b32_e32 v124, 0x10000, v182
	v_sub_u32_sdwa v176, v175, v176 dst_sel:WORD_1 dst_unused:UNUSED_PAD src0_sel:DWORD src1_sel:DWORD
	v_sub_u32_sdwa v180, v177, v180 dst_sel:WORD_1 dst_unused:UNUSED_PAD src0_sel:DWORD src1_sel:DWORD
	v_lshlrev_b32_e32 v119, 8, v119
	v_lshlrev_b32_e32 v174, 8, v174
	v_sub_u32_e32 v120, v177, v120
	v_sub_u32_e32 v124, v175, v124
	v_or_b32_e32 v181, v180, v119
	v_or_b32_e32 v180, v176, v174
	v_and_b32_e32 v120, 0xffff0000, v120
	v_and_b32_e32 v124, 0xffff0000, v124
	v_lshlrev_b32_sdwa v173, v230, v173 dst_sel:DWORD dst_unused:UNUSED_PAD src0_sel:DWORD src1_sel:BYTE_3
	v_lshlrev_b32_sdwa v172, v230, v172 dst_sel:DWORD dst_unused:UNUSED_PAD src0_sel:DWORD src1_sel:BYTE_3
	v_pk_add_f32 v[180:181], v[218:219], v[180:181]
	v_or_b32_e32 v173, v120, v173
	v_or_b32_e32 v172, v124, v172
	v_mov_b32_e32 v120, v125
	v_add_u32_e32 v119, 0x8000, v180
	v_pk_add_f32 v[124:125], v[120:121], v[172:173]
	v_lshrrev_b32_e32 v119, 16, v119
	v_add_u32_e32 v120, 0x8000, v124
	v_pk_mul_f32 v[138:139], v[224:225], v[224:225]
	v_pk_mul_f32 v[136:137], v[122:123], v[122:123]
	v_and_or_b32 v119, v120, s90, v119
	v_pk_mul_f32 v[120:121], v[124:125], v[124:125]
	v_pk_fma_f32 v[138:139], v[222:223], v[222:223], v[138:139]
	v_pk_fma_f32 v[136:137], v[134:135], v[134:135], v[136:137]
	v_pk_fma_f32 v[172:173], v[180:181], v[180:181], v[120:121]
	v_add_u32_e32 v120, 0x8000, v135
	v_lshrrev_b32_e32 v134, 8, v134
	v_lshrrev_b32_e32 v120, 16, v120
	v_add_u32_e32 v121, 0x8000, v123
	v_perm_b32 v122, v122, v134, s94
	v_add_f32_e32 v134, v138, v170
	v_and_or_b32 v120, v121, s90, v120
	v_add_u32_e32 v121, 0x8000, v181
	v_add_f32_e32 v134, v139, v134
	v_lshrrev_b32_e32 v121, 16, v121
	v_add_u32_e32 v174, 0x8000, v125
	v_add_f32_e32 v134, v171, v134
	v_and_or_b32 v121, v174, s90, v121
	v_lshrrev_b32_e32 v174, 8, v181
	v_lshrrev_b32_e32 v175, 8, v180
	v_add_f32_e32 v134, v136, v134
	v_lshrrev_b32_e32 v176, 8, v241
	v_lshrrev_b32_e32 v177, 8, v240
	v_perm_b32 v124, v124, v175, s94
	v_perm_b32 v125, v125, v174, s94
	v_lshrrev_b32_e32 v135, 8, v135
	v_lshrrev_b32_e32 v174, 8, v223
	v_lshrrev_b32_e32 v175, 8, v222
	v_add_f32_e32 v134, v172, v134
	v_perm_b32 v140, v140, v177, s94
	v_perm_b32 v141, v141, v176, s94
	v_perm_b32 v175, v224, v175, s94
	v_perm_b32 v174, v225, v174, s94
	v_perm_b32 v123, v123, v135, s94
	v_add_f32_e32 v134, v137, v134
	global_store_dwordx4 v[178:179], v[118:121], off offset:256
	v_lshl_or_b32 v125, v125, 16, v123
	v_lshl_or_b32 v124, v124, 16, v122
	v_lshl_add_u64 v[118:119], s[34:35], 0, v[216:217]
	v_lshl_or_b32 v123, v141, 16, v174
	v_lshl_or_b32 v122, v140, 16, v175
	v_add_f32_e32 v134, v173, v134
	v_lshl_add_u64 v[118:119], v[118:119], 0, v[194:195]
	global_store_dwordx4 v[118:119], v[122:125], off
	ds_bpermute_b32 v118, v238, v134
	s_waitcnt lgkmcnt(0)
	v_add_f32_e32 v118, v134, v118
	ds_bpermute_b32 v119, v237, v118
	s_and_saveexec_b64 s[54:55], s[40:41]
	s_mov_b32 s80, 0x4b800000
	s_cbranch_execz .LBB0_1202
	s_waitcnt lgkmcnt(0)
	v_add_f32_e32 v118, v118, v119
	v_fma_f32 v118, v118, s80, 0.5
	v_trunc_f32_e32 v118, v118
	v_mul_f32_e32 v119, 0x2f800000, v118
	v_floor_f32_e32 v119, v119
	v_fmac_f32_e32 v118, 0xcf800000, v119
	v_cvt_u32_f32_e32 v118, v118
	v_cvt_u32_f32_e32 v119, v119
	v_lshl_add_u64 v[120:121], v[198:199], 3, s[44:45]
	global_atomic_add_x2 v[120:121], v[118:119], off
